# rolling conversion: exact outstanding-op counts at each wait (separate paths when the previous tile's 4 stores are still younger), so the lookahead is a full 16 loads
# speedup vs baseline: 1.0234x; 1.0029x over previous
.LBB0_1156:
	s_add_i32 s83, s84, 1
	s_cmp_lt_u32 s83, s35
	s_cselect_b64 s[36:37], -1, 0
	s_cmp_ge_u32 s83, s35
	s_cbranch_scc1 .LBB0_1162
	s_cmp_lt_u32 s83, s81
	s_cselect_b32 s20, 0, s81
	s_cselect_b32 s38, s34, s80
	s_lshl_b32 s20, s20, 6
	s_sub_i32 s20, s38, s20
	s_add_i32 s38, s82, s20
	v_add_u32_e32 v0, s38, v56
	v_add_u32_e32 v4, s38, v57
	v_add_u32_e32 v8, s38, v58
	v_ashrrev_i32_e32 v1, 31, v0
	v_ashrrev_i32_e32 v5, 31, v4
	v_ashrrev_i32_e32 v9, 31, v8
	v_lshlrev_b64 v[2:3], 11, v[0:1]
	v_lshlrev_b64 v[0:1], 7, v[0:1]
	v_lshlrev_b64 v[6:7], 11, v[4:5]
	v_lshlrev_b64 v[4:5], 7, v[4:5]
	v_lshlrev_b64 v[10:11], 11, v[8:9]
	v_lshlrev_b64 v[8:9], 7, v[8:9]
	v_lshl_add_u64 v[0:1], v[26:27], 0, v[0:1]
	v_lshl_add_u64 v[4:5], v[30:31], 0, v[4:5]
	v_lshl_add_u64 v[8:9], v[34:35], 0, v[8:9]
	s_ashr_i32 s39, s38, 31
	v_lshl_add_u64 v[2:3], v[42:43], 0, v[2:3]
	v_lshl_add_u64 v[0:1], v[0:1], 0, s[28:29]
	v_lshl_add_u64 v[6:7], v[44:45], 0, v[6:7]
	v_lshl_add_u64 v[4:5], v[4:5], 0, s[28:29]
	v_lshl_add_u64 v[10:11], v[46:47], 0, v[10:11]
	v_lshl_add_u64 v[8:9], v[8:9], 0, s[28:29]
	v_lshl_add_u64 v[12:13], s[38:39], 1, v[24:25]
	v_cndmask_b32_e64 v1, v1, v3, s[6:7]
	v_cndmask_b32_e64 v0, v0, v2, s[6:7]
	v_cndmask_b32_e64 v5, v5, v7, s[10:11]
	v_cndmask_b32_e64 v4, v4, v6, s[10:11]
	v_cndmask_b32_e64 v9, v9, v11, s[14:15]
	v_cndmask_b32_e64 v8, v8, v10, s[14:15]
	v_lshl_add_u64 v[14:15], v[12:13], 0, v[38:39]
	v_lshl_add_u64 v[16:17], v[12:13], 0, v[40:41]
	global_load_dwordx4 v[0:3], v[0:1], off
	s_nop 0
	global_load_dwordx4 v[4:7], v[4:5], off
	s_nop 0
	global_load_dwordx4 v[8:11], v[8:9], off
	s_nop 0
	global_load_dwordx4 v[12:15], v[14:15], off
	s_nop 0
	global_load_dwordx4 v[16:19], v[16:17], off
	s_cmp_eq_u32 s99, 3
	s_cbranch_scc1 .Lp5_st3
	s_cmp_eq_u32 s99, 4
	s_cbranch_scc1 .Lp5_st4
	s_cmp_eq_u32 s99, 1
	s_cbranch_scc1 .Lp5_st1
	s_cmp_gt_i32 s53, 0xbfff
	s_cbranch_scc1 .LBB0_1159
	s_add_i32 s20, s83, 1
	s_cmp_ge_u32 s20, s35
	s_cbranch_scc1 .LBB0_1159
	s_ashr_i32 s20, s53, 10
	s_mul_hi_i32 s38, s20, 0x55555556
	s_lshr_b32 s39, s38, 31
	s_add_i32 s40, s38, s39
	s_mul_i32 s38, s40, 3
	s_sub_i32 s44, s20, s38
	s_lshl_b32 s20, s53, 8
	s_ashr_i32 s45, s44, 31
	s_and_b32 s20, s20, 0x700
	s_lshl_b64 s[38:39], s[44:45], 3
	s_add_u32 s42, s0, s38
	s_addc_u32 s43, s1, s39
	s_ashr_i32 s41, s40, 31
	v_or_b32_e32 v22, s20, v54
	s_cmp_lg_u32 s44, 2
	s_mov_b64 s[46:47], -1
	s_cbranch_scc0 .Lp5_i1_1165
	v_lshlrev_b32_e32 v226, 1, v22
	s_lshl_b64 s[38:39], s[40:41], 23
	v_and_b32_e32 v226, 0xf00, v226
	v_lshl_or_b32 v227, s44, 7, v55
	s_add_u32 s38, s48, s38
	v_add_u32_e32 v226, v227, v226
	s_addc_u32 s39, s49, s39
	s_mov_b64 s[46:47], 0

.Lp5_i2_1168:
	s_lshl_b64 s[44:45], s[44:45], 2
	s_waitcnt lgkmcnt(0)
	s_add_u32 s20, s42, s44
	s_addc_u32 s43, s43, s45
	s_bfe_u32 s44, s53, 0x70003
	s_lshl_b32 s42, s44, 17
	s_add_u32 s42, s20, s42
	s_addc_u32 s43, s43, 0
	v_lshlrev_b32_e32 v224, 2, v224
	v_lshl_add_u64 v[232:233], s[42:43], 0, v[224:225]
	global_load_dwordx4 v[148:151], v224, s[42:43] nt
	s_nop 0
	v_mov_b32_e32 v212, v23
	v_mov_b32_e32 v213, v23
	v_mov_b32_e32 v214, v23
	v_mov_b32_e32 v215, v23
	v_mov_b32_e32 v216, v23
	v_mov_b32_e32 v217, v23
	v_mov_b32_e32 v218, v23
	v_mov_b32_e32 v219, v23
	v_mov_b32_e32 v220, v23
	v_mov_b32_e32 v221, v23
	v_mov_b32_e32 v222, v23
	v_mov_b32_e32 v223, v23
	s_mul_i32 s20, s40, s44
	v_ashrrev_i32_e32 v229, 31, v228
	v_lshl_add_u64 v[228:229], s[20:21], 0, v[228:229]
	v_lshl_add_u64 v[228:229], v[228:229], 4, s[38:39]
	s_mov_b32 s100, s41
	s_addk_i32 s53, 0x400
	s_waitcnt vmcnt(21)
	v_add_co_u32_e32 v152, vcc, s64, v232
	v_addc_co_u32_e32 v153, vcc, 0, v233, vcc
	global_load_dwordx4 v[152:155], v[152:153], off nt
	s_nop 0
	v_mul_f32_e32 v22, s98, v72
	s_waitcnt vmcnt(21)
	v_add_co_u32_e32 v156, vcc, s65, v232
	v_addc_co_u32_e32 v157, vcc, 0, v233, vcc
	global_load_dwordx4 v[156:159], v[156:157], off nt
	s_nop 0
	v_mul_f32_e32 v72, s98, v76
	v_cvt_pk_fp8_f32 v136, v22, v72
	s_waitcnt vmcnt(21)
	v_add_co_u32_e32 v160, vcc, s66, v232
	v_addc_co_u32_e32 v161, vcc, 0, v233, vcc
	global_load_dwordx4 v[160:163], v[160:161], off nt
	s_nop 0
	v_mul_f32_e32 v76, s98, v80
	s_waitcnt vmcnt(21)
	v_add_co_u32_e32 v164, vcc, s67, v232
	v_addc_co_u32_e32 v165, vcc, 0, v233, vcc
	global_load_dwordx4 v[164:167], v[164:165], off nt
	s_nop 0
	v_mul_f32_e32 v80, s98, v84
	s_waitcnt vmcnt(21)
	v_add_co_u32_e32 v168, vcc, s68, v232
	v_addc_co_u32_e32 v169, vcc, 0, v233, vcc
	global_load_dwordx4 v[168:171], v[168:169], off nt
	s_nop 0
	v_mul_f32_e32 v22, s98, v88
	v_cvt_pk_fp8_f32 v136, v76, v80 op_sel:[0,0,1]
	s_waitcnt vmcnt(21)
	v_add_co_u32_e32 v172, vcc, s69, v232
	v_addc_co_u32_e32 v173, vcc, 0, v233, vcc
	global_load_dwordx4 v[172:175], v[172:173], off nt
	s_nop 0
	v_mul_f32_e32 v72, s98, v92
	v_cvt_pk_fp8_f32 v137, v22, v72
	s_waitcnt vmcnt(21)
	v_add_co_u32_e32 v176, vcc, s70, v232
	v_addc_co_u32_e32 v177, vcc, 0, v233, vcc
	global_load_dwordx4 v[176:179], v[176:177], off nt
	s_nop 0
	v_mul_f32_e32 v22, s98, v96
	s_waitcnt vmcnt(21)
	v_add_co_u32_e32 v180, vcc, s71, v232
	v_addc_co_u32_e32 v181, vcc, 0, v233, vcc
	global_load_dwordx4 v[180:183], v[180:181], off nt
	s_nop 0
	v_mul_f32_e32 v72, s98, v100
	v_cvt_pk_fp8_f32 v137, v22, v72 op_sel:[0,0,1]
	s_waitcnt vmcnt(21)
	v_add_co_u32_e32 v184, vcc, s72, v232
	v_addc_co_u32_e32 v185, vcc, 0, v233, vcc
	global_load_dwordx4 v[184:187], v[184:185], off nt
	s_nop 0
	v_mul_f32_e32 v22, s98, v104
	s_waitcnt vmcnt(21)
	v_add_co_u32_e32 v188, vcc, s73, v232
	v_addc_co_u32_e32 v189, vcc, 0, v233, vcc
	global_load_dwordx4 v[188:191], v[188:189], off nt
	s_nop 0
	v_mul_f32_e32 v72, s98, v108
	v_cvt_pk_fp8_f32 v138, v22, v72
	s_waitcnt vmcnt(21)
	v_add_co_u32_e32 v192, vcc, s74, v232
	v_addc_co_u32_e32 v193, vcc, 0, v233, vcc
	global_load_dwordx4 v[192:195], v[192:193], off nt
	s_nop 0
	v_mul_f32_e32 v76, s98, v112
	s_waitcnt vmcnt(21)
	v_add_co_u32_e32 v196, vcc, s75, v232
	v_addc_co_u32_e32 v197, vcc, 0, v233, vcc
	global_load_dwordx4 v[196:199], v[196:197], off nt
	s_nop 0
	v_mul_f32_e32 v80, s98, v116
	s_waitcnt vmcnt(21)
	v_add_co_u32_e32 v200, vcc, s76, v232
	v_addc_co_u32_e32 v201, vcc, 0, v233, vcc
	global_load_dwordx4 v[200:203], v[200:201], off nt
	s_nop 0
	v_mul_f32_e32 v22, s98, v120
	v_cvt_pk_fp8_f32 v138, v76, v80 op_sel:[0,0,1]
	v_mul_f32_e32 v76, s98, v85
	s_waitcnt vmcnt(21)
	v_add_co_u32_e32 v204, vcc, s77, v232
	v_addc_co_u32_e32 v205, vcc, 0, v233, vcc
	global_load_dwordx4 v[204:207], v[204:205], off nt
	s_nop 0
	v_mul_f32_e32 v72, s98, v124
	v_cvt_pk_fp8_f32 v139, v22, v72
	s_waitcnt vmcnt(21)
	v_add_co_u32_e32 v208, vcc, s78, v232
	v_addc_co_u32_e32 v209, vcc, 0, v233, vcc
	global_load_dwordx4 v[208:211], v[208:209], off nt
	s_nop 0
	v_mul_f32_e32 v22, s98, v128
	s_waitcnt vmcnt(21)
	v_mul_f32_e32 v72, s98, v132
	v_cvt_pk_fp8_f32 v139, v22, v72 op_sel:[0,0,1]
	v_mul_f32_e32 v22, s98, v73
	v_mul_f32_e32 v72, s98, v77
	v_cvt_pk_fp8_f32 v140, v22, v72
	v_mul_f32_e32 v22, s98, v89
	v_mul_f32_e32 v72, s98, v93
	v_cvt_pk_fp8_f32 v141, v22, v72
	v_mul_f32_e32 v22, s98, v97
	v_mul_f32_e32 v72, s98, v101
	v_mul_f32_e32 v73, s98, v81
	v_cvt_pk_fp8_f32 v141, v22, v72 op_sel:[0,0,1]
	v_mul_f32_e32 v22, s98, v105
	v_mul_f32_e32 v72, s98, v109
	v_cvt_pk_fp8_f32 v142, v22, v72
	v_mul_f32_e32 v22, s98, v121
	v_mul_f32_e32 v72, s98, v125
	v_cvt_pk_fp8_f32 v143, v22, v72
	v_mul_f32_e32 v22, s98, v129
	v_mul_f32_e32 v72, s98, v133
	v_cvt_pk_fp8_f32 v140, v73, v76 op_sel:[0,0,1]
	v_cvt_pk_fp8_f32 v143, v22, v72 op_sel:[0,0,1]
	v_mul_f32_e32 v22, s98, v74
	v_mul_f32_e32 v72, s98, v78
	v_cvt_pk_fp8_f32 v144, v22, v72
	v_mul_f32_e32 v22, s98, v90
	v_mul_f32_e32 v72, s98, v94
	v_cvt_pk_fp8_f32 v145, v22, v72
	v_mul_f32_e32 v22, s98, v98
	v_mul_f32_e32 v72, s98, v102
	v_mul_f32_e32 v73, s98, v113
	v_cvt_pk_fp8_f32 v145, v22, v72 op_sel:[0,0,1]
	v_mul_f32_e32 v22, s98, v106
	v_mul_f32_e32 v72, s98, v110
	v_cvt_pk_fp8_f32 v146, v22, v72
	v_mul_f32_e32 v22, s98, v122
	v_mul_f32_e32 v72, s98, v126
	v_cvt_pk_fp8_f32 v147, v22, v72
	v_mul_f32_e32 v76, s98, v117
	v_cvt_pk_fp8_f32 v142, v73, v76 op_sel:[0,0,1]
	v_mul_f32_e32 v73, s98, v82
	v_mul_f32_e32 v74, s98, v86
	v_cvt_pk_fp8_f32 v144, v73, v74 op_sel:[0,0,1]
	v_mul_f32_e32 v73, s98, v114
	v_mul_f32_e32 v74, s98, v118
	v_mul_f32_e32 v22, s98, v130
	v_mul_f32_e32 v72, s98, v134
	v_cvt_pk_fp8_f32 v146, v73, v74 op_sel:[0,0,1]
	v_cvt_pk_fp8_f32 v147, v22, v72 op_sel:[0,0,1]
	v_mul_f32_e32 v22, s98, v75
	v_mul_f32_e32 v73, s98, v79
	v_mov_b32_e32 v72, v23
	v_cvt_pk_fp8_f32 v72, v22, v73
	v_mul_f32_e32 v22, s98, v91
	v_mul_f32_e32 v76, s98, v95
	v_mov_b32_e32 v73, v23
	v_cvt_pk_fp8_f32 v73, v22, v76
	v_mul_f32_e32 v74, s98, v83
	v_mul_f32_e32 v75, s98, v87
	v_cvt_pk_fp8_f32 v72, v74, v75 op_sel:[0,0,1]
	v_mul_f32_e32 v22, s98, v99
	v_mul_f32_e32 v74, s98, v103
	v_cvt_pk_fp8_f32 v73, v22, v74 op_sel:[0,0,1]
	v_mul_f32_e32 v22, s98, v107
	v_mul_f32_e32 v75, s98, v111
	v_mov_b32_e32 v74, v23
	v_cvt_pk_fp8_f32 v74, v22, v75
	v_mul_f32_e32 v22, s98, v123
	v_mul_f32_e32 v78, s98, v127
	v_mov_b32_e32 v75, v23
	v_cvt_pk_fp8_f32 v75, v22, v78
	v_mul_f32_e32 v76, s98, v115
	v_mul_f32_e32 v77, s98, v119
	v_cvt_pk_fp8_f32 v74, v76, v77 op_sel:[0,0,1]
	v_mul_f32_e32 v22, s98, v131
	v_mul_f32_e32 v76, s98, v135
	v_cvt_pk_fp8_f32 v75, v22, v76 op_sel:[0,0,1]
	global_store_dwordx4 v[226:227], v[136:139], off
	global_store_dwordx4 v[226:227], v[140:143], off offset:16
	global_store_dwordx4 v[226:227], v[144:147], off offset:32
	global_store_dwordx4 v[226:227], v[72:75], off offset:48
	s_mov_b32 s99, 4
	s_waitcnt vmcnt(20)
	s_andn2_b32 s20, 1, s84
	s_mul_i32 s20, s20, 0xa800
	s_add_i32 s20, s20, 0
	v_add3_u32 v22, s20, v61, v62
	ds_write_b128 v22, v[0:3]
	v_add3_u32 v22, s20, v63, v64
	ds_write_b128 v22, v[4:7]
	v_add3_u32 v22, s20, v65, v66
	ds_write_b128 v22, v[8:11]
	v_add_u32_e32 v22, s20, v20
	v_add3_u32 v48, v22, v67, s63
	v_add3_u32 v22, v22, v68, s63
	ds_write2_b64 v48, v[12:13], v[14:15] offset1:1
	ds_write2_b64 v22, v[16:17], v[18:19] offset1:1
	s_branch .LBB0_1160
.Lp5_st1c:
	s_waitcnt vmcnt(20)
	v_mul_f32_e32 v22, s98, v72
	s_waitcnt vmcnt(19)
	v_mul_f32_e32 v72, s98, v76
	v_cvt_pk_fp8_f32 v136, v22, v72
	s_waitcnt vmcnt(18)
	v_mul_f32_e32 v76, s98, v80
	s_waitcnt vmcnt(17)
	v_mul_f32_e32 v80, s98, v84
	s_waitcnt vmcnt(16)
	v_mul_f32_e32 v22, s98, v88
	v_cvt_pk_fp8_f32 v136, v76, v80 op_sel:[0,0,1]
	s_waitcnt vmcnt(15)
	v_mul_f32_e32 v72, s98, v92
	v_cvt_pk_fp8_f32 v137, v22, v72
	s_waitcnt vmcnt(14)
	v_mul_f32_e32 v22, s98, v96
	s_waitcnt vmcnt(13)
	v_mul_f32_e32 v72, s98, v100
	v_cvt_pk_fp8_f32 v137, v22, v72 op_sel:[0,0,1]
	s_waitcnt vmcnt(12)
	v_mul_f32_e32 v22, s98, v104
	s_waitcnt vmcnt(11)
	v_mul_f32_e32 v72, s98, v108
	v_cvt_pk_fp8_f32 v138, v22, v72
	s_waitcnt vmcnt(10)
	v_mul_f32_e32 v76, s98, v112
	s_waitcnt vmcnt(9)
	v_mul_f32_e32 v80, s98, v116
	s_waitcnt vmcnt(8)
	v_mul_f32_e32 v22, s98, v120
	v_cvt_pk_fp8_f32 v138, v76, v80 op_sel:[0,0,1]
	v_mul_f32_e32 v76, s98, v85
	s_waitcnt vmcnt(7)
	v_mul_f32_e32 v72, s98, v124
	v_cvt_pk_fp8_f32 v139, v22, v72
	s_waitcnt vmcnt(6)
	v_mul_f32_e32 v22, s98, v128
	s_waitcnt vmcnt(5)
	v_mul_f32_e32 v72, s98, v132
	v_cvt_pk_fp8_f32 v139, v22, v72 op_sel:[0,0,1]
	v_mul_f32_e32 v22, s98, v73
	v_mul_f32_e32 v72, s98, v77
	v_cvt_pk_fp8_f32 v140, v22, v72
	v_mul_f32_e32 v22, s98, v89
	v_mul_f32_e32 v72, s98, v93
	v_cvt_pk_fp8_f32 v141, v22, v72
	v_mul_f32_e32 v22, s98, v97
	v_mul_f32_e32 v72, s98, v101
	v_mul_f32_e32 v73, s98, v81
	v_cvt_pk_fp8_f32 v141, v22, v72 op_sel:[0,0,1]
	v_mul_f32_e32 v22, s98, v105
	v_mul_f32_e32 v72, s98, v109
	v_cvt_pk_fp8_f32 v142, v22, v72
	v_mul_f32_e32 v22, s98, v121
	v_mul_f32_e32 v72, s98, v125
	v_cvt_pk_fp8_f32 v143, v22, v72
	v_mul_f32_e32 v22, s98, v129
	v_mul_f32_e32 v72, s98, v133
	v_cvt_pk_fp8_f32 v140, v73, v76 op_sel:[0,0,1]
	v_cvt_pk_fp8_f32 v143, v22, v72 op_sel:[0,0,1]
	v_mul_f32_e32 v22, s98, v74
	v_mul_f32_e32 v72, s98, v78
	v_cvt_pk_fp8_f32 v144, v22, v72
	v_mul_f32_e32 v22, s98, v90
	v_mul_f32_e32 v72, s98, v94
	v_cvt_pk_fp8_f32 v145, v22, v72
	v_mul_f32_e32 v22, s98, v98
	v_mul_f32_e32 v72, s98, v102
	v_mul_f32_e32 v73, s98, v113
	v_cvt_pk_fp8_f32 v145, v22, v72 op_sel:[0,0,1]
	v_mul_f32_e32 v22, s98, v106
	v_mul_f32_e32 v72, s98, v110
	v_cvt_pk_fp8_f32 v146, v22, v72
	v_mul_f32_e32 v22, s98, v122
	v_mul_f32_e32 v72, s98, v126
	v_cvt_pk_fp8_f32 v147, v22, v72
	v_mul_f32_e32 v76, s98, v117
	v_cvt_pk_fp8_f32 v142, v73, v76 op_sel:[0,0,1]
	v_mul_f32_e32 v73, s98, v82
	v_mul_f32_e32 v74, s98, v86
	v_cvt_pk_fp8_f32 v144, v73, v74 op_sel:[0,0,1]
	v_mul_f32_e32 v73, s98, v114
	v_mul_f32_e32 v74, s98, v118
	v_mul_f32_e32 v22, s98, v130
	v_mul_f32_e32 v72, s98, v134
	v_cvt_pk_fp8_f32 v146, v73, v74 op_sel:[0,0,1]
	v_cvt_pk_fp8_f32 v147, v22, v72 op_sel:[0,0,1]
	v_mul_f32_e32 v22, s98, v75
	v_mul_f32_e32 v73, s98, v79
	v_mov_b32_e32 v72, v23
	v_cvt_pk_fp8_f32 v72, v22, v73
	v_mul_f32_e32 v22, s98, v91
	v_mul_f32_e32 v76, s98, v95
	v_mov_b32_e32 v73, v23
	v_cvt_pk_fp8_f32 v73, v22, v76
	v_mul_f32_e32 v74, s98, v83
	v_mul_f32_e32 v75, s98, v87
	v_cvt_pk_fp8_f32 v72, v74, v75 op_sel:[0,0,1]
	v_mul_f32_e32 v22, s98, v99
	v_mul_f32_e32 v74, s98, v103
	v_cvt_pk_fp8_f32 v73, v22, v74 op_sel:[0,0,1]
	v_mul_f32_e32 v22, s98, v107
	v_mul_f32_e32 v75, s98, v111
	v_mov_b32_e32 v74, v23
	v_cvt_pk_fp8_f32 v74, v22, v75
	v_mul_f32_e32 v22, s98, v123
	v_mul_f32_e32 v78, s98, v127
	v_mov_b32_e32 v75, v23
	v_cvt_pk_fp8_f32 v75, v22, v78
	v_mul_f32_e32 v76, s98, v115
	v_mul_f32_e32 v77, s98, v119
	v_cvt_pk_fp8_f32 v74, v76, v77 op_sel:[0,0,1]
	v_mul_f32_e32 v22, s98, v131
	v_mul_f32_e32 v76, s98, v135
	v_cvt_pk_fp8_f32 v75, v22, v76 op_sel:[0,0,1]
	global_store_dwordx4 v[226:227], v[136:139], off
	global_store_dwordx4 v[226:227], v[140:143], off offset:16
	global_store_dwordx4 v[226:227], v[144:147], off offset:32
	global_store_dwordx4 v[226:227], v[72:75], off offset:48
	s_mov_b32 s99, 0
	s_waitcnt vmcnt(4)
	s_andn2_b32 s20, 1, s84
	s_mul_i32 s20, s20, 0xa800
	s_add_i32 s20, s20, 0
	v_add3_u32 v22, s20, v61, v62
	ds_write_b128 v22, v[0:3]
	v_add3_u32 v22, s20, v63, v64
	ds_write_b128 v22, v[4:7]
	v_add3_u32 v22, s20, v65, v66
	ds_write_b128 v22, v[8:11]
	v_add_u32_e32 v22, s20, v20
	v_add3_u32 v48, v22, v67, s63
	v_add3_u32 v22, v22, v68, s63
	ds_write2_b64 v48, v[12:13], v[14:15] offset1:1
	ds_write2_b64 v22, v[16:17], v[18:19] offset1:1
	s_branch .LBB0_1160
.Lp5_st3:
	s_cmp_gt_i32 s53, 0xbfff
	s_cbranch_scc1 .Lp5_st3c
	s_add_i32 s20, s83, 1
	s_cmp_ge_u32 s20, s35
	s_cbranch_scc1 .Lp5_st3c
	v_mov_b32_e32 v225, 0
	s_ashr_i32 s20, s53, 10
	s_mul_hi_i32 s38, s20, 0x55555556
	s_lshr_b32 s39, s38, 31
	s_add_i32 s40, s38, s39
	s_mul_i32 s38, s40, 3
	s_sub_i32 s44, s20, s38
	s_lshl_b32 s20, s53, 8
	s_ashr_i32 s45, s44, 31
	s_and_b32 s20, s20, 0x700
	s_lshl_b64 s[38:39], s[44:45], 3
	s_add_u32 s42, s0, s38
	s_addc_u32 s43, s1, s39
	s_ashr_i32 s41, s40, 31
	v_or_b32_e32 v224, s20, v54
	s_cmp_lg_u32 s44, 2
	s_mov_b64 s[46:47], -1
	s_cbranch_scc0 .Lp5_i3_1165
	v_lshlrev_b32_e32 v228, 1, v224
	s_lshl_b64 s[38:39], s[40:41], 23
	v_and_b32_e32 v228, 0xf00, v228
	v_lshl_or_b32 v229, s44, 7, v55
	s_add_u32 s38, s48, s38
	v_add_u32_e32 v228, v229, v228
	s_addc_u32 s39, s49, s39
	s_mov_b64 s[46:47], 0

.Lp5_i3_1168:
	s_lshl_b64 s[44:45], s[44:45], 2
	s_waitcnt lgkmcnt(0)
	s_add_u32 s20, s42, s44
	s_addc_u32 s43, s43, s45
	s_bfe_u32 s44, s53, 0x70003
	s_lshl_b32 s42, s44, 17
	s_add_u32 s42, s20, s42
	s_addc_u32 s43, s43, 0
	v_lshlrev_b32_e32 v224, 2, v224
	v_lshl_add_u64 v[232:233], s[42:43], 0, v[224:225]
	global_load_dwordx4 v[148:151], v224, s[42:43] nt
	s_nop 0
	v_mov_b32_e32 v212, v23
	v_mov_b32_e32 v213, v23
	v_mov_b32_e32 v214, v23
	v_mov_b32_e32 v215, v23
	v_mov_b32_e32 v216, v23
	v_mov_b32_e32 v217, v23
	v_mov_b32_e32 v218, v23
	v_mov_b32_e32 v219, v23
	v_mov_b32_e32 v220, v23
	v_mov_b32_e32 v221, v23
	v_mov_b32_e32 v222, v23
	v_mov_b32_e32 v223, v23
	s_mul_i32 s20, s40, s44
	v_ashrrev_i32_e32 v229, 31, v228
	v_lshl_add_u64 v[228:229], s[20:21], 0, v[228:229]
	v_lshl_add_u64 v[228:229], v[228:229], 4, s[38:39]
	s_mov_b32 s100, s41
	s_addk_i32 s53, 0x400
	s_waitcnt vmcnt(25)
	v_add_co_u32_e32 v152, vcc, s64, v232
	v_addc_co_u32_e32 v153, vcc, 0, v233, vcc
	global_load_dwordx4 v[152:155], v[152:153], off nt
	s_nop 0
	v_mul_f32_e32 v22, s98, v72
	s_waitcnt vmcnt(25)
	v_add_co_u32_e32 v156, vcc, s65, v232
	v_addc_co_u32_e32 v157, vcc, 0, v233, vcc
	global_load_dwordx4 v[156:159], v[156:157], off nt
	s_nop 0
	v_mul_f32_e32 v72, s98, v76
	v_cvt_pk_fp8_f32 v136, v22, v72
	s_waitcnt vmcnt(25)
	v_add_co_u32_e32 v160, vcc, s66, v232
	v_addc_co_u32_e32 v161, vcc, 0, v233, vcc
	global_load_dwordx4 v[160:163], v[160:161], off nt
	s_nop 0
	v_mul_f32_e32 v76, s98, v80
	s_waitcnt vmcnt(25)
	v_add_co_u32_e32 v164, vcc, s67, v232
	v_addc_co_u32_e32 v165, vcc, 0, v233, vcc
	global_load_dwordx4 v[164:167], v[164:165], off nt
	s_nop 0
	v_mul_f32_e32 v80, s98, v84
	s_waitcnt vmcnt(25)
	v_add_co_u32_e32 v168, vcc, s68, v232
	v_addc_co_u32_e32 v169, vcc, 0, v233, vcc
	global_load_dwordx4 v[168:171], v[168:169], off nt
	s_nop 0
	v_mul_f32_e32 v22, s98, v88
	v_cvt_pk_fp8_f32 v136, v76, v80 op_sel:[0,0,1]
	s_waitcnt vmcnt(25)
	v_add_co_u32_e32 v172, vcc, s69, v232
	v_addc_co_u32_e32 v173, vcc, 0, v233, vcc
	global_load_dwordx4 v[172:175], v[172:173], off nt
	s_nop 0
	v_mul_f32_e32 v72, s98, v92
	v_cvt_pk_fp8_f32 v137, v22, v72
	s_waitcnt vmcnt(25)
	v_add_co_u32_e32 v176, vcc, s70, v232
	v_addc_co_u32_e32 v177, vcc, 0, v233, vcc
	global_load_dwordx4 v[176:179], v[176:177], off nt
	s_nop 0
	v_mul_f32_e32 v22, s98, v96
	s_waitcnt vmcnt(25)
	v_add_co_u32_e32 v180, vcc, s71, v232
	v_addc_co_u32_e32 v181, vcc, 0, v233, vcc
	global_load_dwordx4 v[180:183], v[180:181], off nt
	s_nop 0
	v_mul_f32_e32 v72, s98, v100
	v_cvt_pk_fp8_f32 v137, v22, v72 op_sel:[0,0,1]
	s_waitcnt vmcnt(25)
	v_add_co_u32_e32 v184, vcc, s72, v232
	v_addc_co_u32_e32 v185, vcc, 0, v233, vcc
	global_load_dwordx4 v[184:187], v[184:185], off nt
	s_nop 0
	v_mul_f32_e32 v22, s98, v104
	s_waitcnt vmcnt(25)
	v_add_co_u32_e32 v188, vcc, s73, v232
	v_addc_co_u32_e32 v189, vcc, 0, v233, vcc
	global_load_dwordx4 v[188:191], v[188:189], off nt
	s_nop 0
	v_mul_f32_e32 v72, s98, v108
	v_cvt_pk_fp8_f32 v138, v22, v72
	s_waitcnt vmcnt(25)
	v_add_co_u32_e32 v192, vcc, s74, v232
	v_addc_co_u32_e32 v193, vcc, 0, v233, vcc
	global_load_dwordx4 v[192:195], v[192:193], off nt
	s_nop 0
	v_mul_f32_e32 v76, s98, v112
	s_waitcnt vmcnt(25)
	v_add_co_u32_e32 v196, vcc, s75, v232
	v_addc_co_u32_e32 v197, vcc, 0, v233, vcc
	global_load_dwordx4 v[196:199], v[196:197], off nt
	s_nop 0
	v_mul_f32_e32 v80, s98, v116
	s_waitcnt vmcnt(25)
	v_add_co_u32_e32 v200, vcc, s76, v232
	v_addc_co_u32_e32 v201, vcc, 0, v233, vcc
	global_load_dwordx4 v[200:203], v[200:201], off nt
	s_nop 0
	v_mul_f32_e32 v22, s98, v120
	v_cvt_pk_fp8_f32 v138, v76, v80 op_sel:[0,0,1]
	v_mul_f32_e32 v76, s98, v85
	s_waitcnt vmcnt(25)
	v_add_co_u32_e32 v204, vcc, s77, v232
	v_addc_co_u32_e32 v205, vcc, 0, v233, vcc
	global_load_dwordx4 v[204:207], v[204:205], off nt
	s_nop 0
	v_mul_f32_e32 v72, s98, v124
	v_cvt_pk_fp8_f32 v139, v22, v72
	s_waitcnt vmcnt(25)
	v_add_co_u32_e32 v208, vcc, s78, v232
	v_addc_co_u32_e32 v209, vcc, 0, v233, vcc
	global_load_dwordx4 v[208:211], v[208:209], off nt
	s_nop 0
	v_mul_f32_e32 v22, s98, v128
	s_waitcnt vmcnt(25)
	v_mul_f32_e32 v72, s98, v132
	v_cvt_pk_fp8_f32 v139, v22, v72 op_sel:[0,0,1]
	v_mul_f32_e32 v22, s98, v73
	v_mul_f32_e32 v72, s98, v77
	v_cvt_pk_fp8_f32 v140, v22, v72
	v_mul_f32_e32 v22, s98, v89
	v_mul_f32_e32 v72, s98, v93
	v_cvt_pk_fp8_f32 v141, v22, v72
	v_mul_f32_e32 v22, s98, v97
	v_mul_f32_e32 v72, s98, v101
	v_mul_f32_e32 v73, s98, v81
	v_cvt_pk_fp8_f32 v141, v22, v72 op_sel:[0,0,1]
	v_mul_f32_e32 v22, s98, v105
	v_mul_f32_e32 v72, s98, v109
	v_cvt_pk_fp8_f32 v142, v22, v72
	v_mul_f32_e32 v22, s98, v121
	v_mul_f32_e32 v72, s98, v125
	v_cvt_pk_fp8_f32 v143, v22, v72
	v_mul_f32_e32 v22, s98, v129
	v_mul_f32_e32 v72, s98, v133
	v_cvt_pk_fp8_f32 v140, v73, v76 op_sel:[0,0,1]
	v_cvt_pk_fp8_f32 v143, v22, v72 op_sel:[0,0,1]
	v_mul_f32_e32 v22, s98, v74
	v_mul_f32_e32 v72, s98, v78
	v_cvt_pk_fp8_f32 v144, v22, v72
	v_mul_f32_e32 v22, s98, v90
	v_mul_f32_e32 v72, s98, v94
	v_cvt_pk_fp8_f32 v145, v22, v72
	v_mul_f32_e32 v22, s98, v98
	v_mul_f32_e32 v72, s98, v102
	v_mul_f32_e32 v73, s98, v113
	v_cvt_pk_fp8_f32 v145, v22, v72 op_sel:[0,0,1]
	v_mul_f32_e32 v22, s98, v106
	v_mul_f32_e32 v72, s98, v110
	v_cvt_pk_fp8_f32 v146, v22, v72
	v_mul_f32_e32 v22, s98, v122
	v_mul_f32_e32 v72, s98, v126
	v_cvt_pk_fp8_f32 v147, v22, v72
	v_mul_f32_e32 v76, s98, v117
	v_cvt_pk_fp8_f32 v142, v73, v76 op_sel:[0,0,1]
	v_mul_f32_e32 v73, s98, v82
	v_mul_f32_e32 v74, s98, v86
	v_cvt_pk_fp8_f32 v144, v73, v74 op_sel:[0,0,1]
	v_mul_f32_e32 v73, s98, v114
	v_mul_f32_e32 v74, s98, v118
	v_mul_f32_e32 v22, s98, v130
	v_mul_f32_e32 v72, s98, v134
	v_cvt_pk_fp8_f32 v146, v73, v74 op_sel:[0,0,1]
	v_cvt_pk_fp8_f32 v147, v22, v72 op_sel:[0,0,1]
	v_mul_f32_e32 v22, s98, v75
	v_mul_f32_e32 v73, s98, v79
	v_mov_b32_e32 v72, v23
	v_cvt_pk_fp8_f32 v72, v22, v73
	v_mul_f32_e32 v22, s98, v91
	v_mul_f32_e32 v76, s98, v95
	v_mov_b32_e32 v73, v23
	v_cvt_pk_fp8_f32 v73, v22, v76
	v_mul_f32_e32 v74, s98, v83
	v_mul_f32_e32 v75, s98, v87
	v_cvt_pk_fp8_f32 v72, v74, v75 op_sel:[0,0,1]
	v_mul_f32_e32 v22, s98, v99
	v_mul_f32_e32 v74, s98, v103
	v_cvt_pk_fp8_f32 v73, v22, v74 op_sel:[0,0,1]
	v_mul_f32_e32 v22, s98, v107
	v_mul_f32_e32 v75, s98, v111
	v_mov_b32_e32 v74, v23
	v_cvt_pk_fp8_f32 v74, v22, v75
	v_mul_f32_e32 v22, s98, v123
	v_mul_f32_e32 v78, s98, v127
	v_mov_b32_e32 v75, v23
	v_cvt_pk_fp8_f32 v75, v22, v78
	v_mul_f32_e32 v76, s98, v115
	v_mul_f32_e32 v77, s98, v119
	v_cvt_pk_fp8_f32 v74, v76, v77 op_sel:[0,0,1]
	v_mul_f32_e32 v22, s98, v131
	v_mul_f32_e32 v76, s98, v135
	v_cvt_pk_fp8_f32 v75, v22, v76 op_sel:[0,0,1]
	global_store_dwordx4 v[226:227], v[136:139], off
	global_store_dwordx4 v[226:227], v[140:143], off offset:16
	global_store_dwordx4 v[226:227], v[144:147], off offset:32
	global_store_dwordx4 v[226:227], v[72:75], off offset:48
	s_mov_b32 s99, 4
	s_waitcnt vmcnt(20)
	s_andn2_b32 s20, 1, s84
	s_mul_i32 s20, s20, 0xa800
	s_add_i32 s20, s20, 0
	v_add3_u32 v22, s20, v61, v62
	ds_write_b128 v22, v[0:3]
	v_add3_u32 v22, s20, v63, v64
	ds_write_b128 v22, v[4:7]
	v_add3_u32 v22, s20, v65, v66
	ds_write_b128 v22, v[8:11]
	v_add_u32_e32 v22, s20, v20
	v_add3_u32 v48, v22, v67, s63
	v_add3_u32 v22, v22, v68, s63
	ds_write2_b64 v48, v[12:13], v[14:15] offset1:1
	ds_write2_b64 v22, v[16:17], v[18:19] offset1:1
	s_branch .LBB0_1160
.Lp5_st3c:
	s_waitcnt vmcnt(24)
	v_mul_f32_e32 v22, s98, v72
	s_waitcnt vmcnt(23)
	v_mul_f32_e32 v72, s98, v76
	v_cvt_pk_fp8_f32 v136, v22, v72
	s_waitcnt vmcnt(22)
	v_mul_f32_e32 v76, s98, v80
	s_waitcnt vmcnt(21)
	v_mul_f32_e32 v80, s98, v84
	s_waitcnt vmcnt(20)
	v_mul_f32_e32 v22, s98, v88
	v_cvt_pk_fp8_f32 v136, v76, v80 op_sel:[0,0,1]
	s_waitcnt vmcnt(19)
	v_mul_f32_e32 v72, s98, v92
	v_cvt_pk_fp8_f32 v137, v22, v72
	s_waitcnt vmcnt(18)
	v_mul_f32_e32 v22, s98, v96
	s_waitcnt vmcnt(17)
	v_mul_f32_e32 v72, s98, v100
	v_cvt_pk_fp8_f32 v137, v22, v72 op_sel:[0,0,1]
	s_waitcnt vmcnt(16)
	v_mul_f32_e32 v22, s98, v104
	s_waitcnt vmcnt(15)
	v_mul_f32_e32 v72, s98, v108
	v_cvt_pk_fp8_f32 v138, v22, v72
	s_waitcnt vmcnt(14)
	v_mul_f32_e32 v76, s98, v112
	s_waitcnt vmcnt(13)
	v_mul_f32_e32 v80, s98, v116
	s_waitcnt vmcnt(12)
	v_mul_f32_e32 v22, s98, v120
	v_cvt_pk_fp8_f32 v138, v76, v80 op_sel:[0,0,1]
	v_mul_f32_e32 v76, s98, v85
	s_waitcnt vmcnt(11)
	v_mul_f32_e32 v72, s98, v124
	v_cvt_pk_fp8_f32 v139, v22, v72
	s_waitcnt vmcnt(10)
	v_mul_f32_e32 v22, s98, v128
	s_waitcnt vmcnt(9)
	v_mul_f32_e32 v72, s98, v132
	v_cvt_pk_fp8_f32 v139, v22, v72 op_sel:[0,0,1]
	v_mul_f32_e32 v22, s98, v73
	v_mul_f32_e32 v72, s98, v77
	v_cvt_pk_fp8_f32 v140, v22, v72
	v_mul_f32_e32 v22, s98, v89
	v_mul_f32_e32 v72, s98, v93
	v_cvt_pk_fp8_f32 v141, v22, v72
	v_mul_f32_e32 v22, s98, v97
	v_mul_f32_e32 v72, s98, v101
	v_mul_f32_e32 v73, s98, v81
	v_cvt_pk_fp8_f32 v141, v22, v72 op_sel:[0,0,1]
	v_mul_f32_e32 v22, s98, v105
	v_mul_f32_e32 v72, s98, v109
	v_cvt_pk_fp8_f32 v142, v22, v72
	v_mul_f32_e32 v22, s98, v121
	v_mul_f32_e32 v72, s98, v125
	v_cvt_pk_fp8_f32 v143, v22, v72
	v_mul_f32_e32 v22, s98, v129
	v_mul_f32_e32 v72, s98, v133
	v_cvt_pk_fp8_f32 v140, v73, v76 op_sel:[0,0,1]
	v_cvt_pk_fp8_f32 v143, v22, v72 op_sel:[0,0,1]
	v_mul_f32_e32 v22, s98, v74
	v_mul_f32_e32 v72, s98, v78
	v_cvt_pk_fp8_f32 v144, v22, v72
	v_mul_f32_e32 v22, s98, v90
	v_mul_f32_e32 v72, s98, v94
	v_cvt_pk_fp8_f32 v145, v22, v72
	v_mul_f32_e32 v22, s98, v98
	v_mul_f32_e32 v72, s98, v102
	v_mul_f32_e32 v73, s98, v113
	v_cvt_pk_fp8_f32 v145, v22, v72 op_sel:[0,0,1]
	v_mul_f32_e32 v22, s98, v106
	v_mul_f32_e32 v72, s98, v110
	v_cvt_pk_fp8_f32 v146, v22, v72
	v_mul_f32_e32 v22, s98, v122
	v_mul_f32_e32 v72, s98, v126
	v_cvt_pk_fp8_f32 v147, v22, v72
	v_mul_f32_e32 v76, s98, v117
	v_cvt_pk_fp8_f32 v142, v73, v76 op_sel:[0,0,1]
	v_mul_f32_e32 v73, s98, v82
	v_mul_f32_e32 v74, s98, v86
	v_cvt_pk_fp8_f32 v144, v73, v74 op_sel:[0,0,1]
	v_mul_f32_e32 v73, s98, v114
	v_mul_f32_e32 v74, s98, v118
	v_mul_f32_e32 v22, s98, v130
	v_mul_f32_e32 v72, s98, v134
	v_cvt_pk_fp8_f32 v146, v73, v74 op_sel:[0,0,1]
	v_cvt_pk_fp8_f32 v147, v22, v72 op_sel:[0,0,1]
	v_mul_f32_e32 v22, s98, v75
	v_mul_f32_e32 v73, s98, v79
	v_mov_b32_e32 v72, v23
	v_cvt_pk_fp8_f32 v72, v22, v73
	v_mul_f32_e32 v22, s98, v91
	v_mul_f32_e32 v76, s98, v95
	v_mov_b32_e32 v73, v23
	v_cvt_pk_fp8_f32 v73, v22, v76
	v_mul_f32_e32 v74, s98, v83
	v_mul_f32_e32 v75, s98, v87
	v_cvt_pk_fp8_f32 v72, v74, v75 op_sel:[0,0,1]
	v_mul_f32_e32 v22, s98, v99
	v_mul_f32_e32 v74, s98, v103
	v_cvt_pk_fp8_f32 v73, v22, v74 op_sel:[0,0,1]
	v_mul_f32_e32 v22, s98, v107
	v_mul_f32_e32 v75, s98, v111
	v_mov_b32_e32 v74, v23
	v_cvt_pk_fp8_f32 v74, v22, v75
	v_mul_f32_e32 v22, s98, v123
	v_mul_f32_e32 v78, s98, v127
	v_mov_b32_e32 v75, v23
	v_cvt_pk_fp8_f32 v75, v22, v78
	v_mul_f32_e32 v76, s98, v115
	v_mul_f32_e32 v77, s98, v119
	v_cvt_pk_fp8_f32 v74, v76, v77 op_sel:[0,0,1]
	v_mul_f32_e32 v22, s98, v131
	v_mul_f32_e32 v76, s98, v135
	v_cvt_pk_fp8_f32 v75, v22, v76 op_sel:[0,0,1]
	global_store_dwordx4 v[226:227], v[136:139], off
	global_store_dwordx4 v[226:227], v[140:143], off offset:16
	global_store_dwordx4 v[226:227], v[144:147], off offset:32
	global_store_dwordx4 v[226:227], v[72:75], off offset:48
	s_mov_b32 s99, 0
	s_waitcnt vmcnt(4)
	s_andn2_b32 s20, 1, s84
	s_mul_i32 s20, s20, 0xa800
	s_add_i32 s20, s20, 0
	v_add3_u32 v22, s20, v61, v62
	ds_write_b128 v22, v[0:3]
	v_add3_u32 v22, s20, v63, v64
	ds_write_b128 v22, v[4:7]
	v_add3_u32 v22, s20, v65, v66
	ds_write_b128 v22, v[8:11]
	v_add_u32_e32 v22, s20, v20
	v_add3_u32 v48, v22, v67, s63
	v_add3_u32 v22, v22, v68, s63
	ds_write2_b64 v48, v[12:13], v[14:15] offset1:1
	ds_write2_b64 v22, v[16:17], v[18:19] offset1:1
	s_branch .LBB0_1160

.Lp5_i4_1168:
	s_lshl_b64 s[44:45], s[44:45], 2
	s_waitcnt lgkmcnt(0)
	s_add_u32 s20, s42, s44
	s_addc_u32 s43, s43, s45
	s_bfe_u32 s44, s53, 0x70003
	s_lshl_b32 s42, s44, 17
	s_add_u32 s42, s20, s42
	s_addc_u32 s43, s43, 0
	v_lshlrev_b32_e32 v22, 2, v22
	v_lshl_add_u64 v[230:231], s[42:43], 0, v[22:23]
	global_load_dwordx4 v[72:75], v22, s[42:43] nt
	s_nop 0
	v_mov_b32_e32 v136, v23
	v_mov_b32_e32 v137, v23
	v_mov_b32_e32 v138, v23
	v_mov_b32_e32 v139, v23
	v_mov_b32_e32 v140, v23
	v_mov_b32_e32 v141, v23
	v_mov_b32_e32 v142, v23
	v_mov_b32_e32 v143, v23
	v_mov_b32_e32 v144, v23
	v_mov_b32_e32 v145, v23
	v_mov_b32_e32 v146, v23
	v_mov_b32_e32 v147, v23
	s_mul_i32 s20, s40, s44
	v_ashrrev_i32_e32 v227, 31, v226
	v_lshl_add_u64 v[226:227], s[20:21], 0, v[226:227]
	v_lshl_add_u64 v[226:227], v[226:227], 4, s[38:39]
	s_mov_b32 s98, s41
	s_addk_i32 s53, 0x400
	s_waitcnt vmcnt(25)
	v_add_co_u32_e32 v76, vcc, s64, v230
	v_addc_co_u32_e32 v77, vcc, 0, v231, vcc
	global_load_dwordx4 v[76:79], v[76:77], off nt
	s_nop 0
	v_mul_f32_e32 v224, s100, v148
	s_waitcnt vmcnt(25)
	v_add_co_u32_e32 v80, vcc, s65, v230
	v_addc_co_u32_e32 v81, vcc, 0, v231, vcc
	global_load_dwordx4 v[80:83], v[80:81], off nt
	s_nop 0
	v_mul_f32_e32 v148, s100, v152
	v_cvt_pk_fp8_f32 v212, v224, v148
	s_waitcnt vmcnt(25)
	v_add_co_u32_e32 v84, vcc, s66, v230
	v_addc_co_u32_e32 v85, vcc, 0, v231, vcc
	global_load_dwordx4 v[84:87], v[84:85], off nt
	s_nop 0
	v_mul_f32_e32 v152, s100, v156
	s_waitcnt vmcnt(25)
	v_add_co_u32_e32 v88, vcc, s67, v230
	v_addc_co_u32_e32 v89, vcc, 0, v231, vcc
	global_load_dwordx4 v[88:91], v[88:89], off nt
	s_nop 0
	v_mul_f32_e32 v156, s100, v160
	s_waitcnt vmcnt(25)
	v_add_co_u32_e32 v92, vcc, s68, v230
	v_addc_co_u32_e32 v93, vcc, 0, v231, vcc
	global_load_dwordx4 v[92:95], v[92:93], off nt
	s_nop 0
	v_mul_f32_e32 v224, s100, v164
	v_cvt_pk_fp8_f32 v212, v152, v156 op_sel:[0,0,1]
	s_waitcnt vmcnt(25)
	v_add_co_u32_e32 v96, vcc, s69, v230
	v_addc_co_u32_e32 v97, vcc, 0, v231, vcc
	global_load_dwordx4 v[96:99], v[96:97], off nt
	s_nop 0
	v_mul_f32_e32 v148, s100, v168
	v_cvt_pk_fp8_f32 v213, v224, v148
	s_waitcnt vmcnt(25)
	v_add_co_u32_e32 v100, vcc, s70, v230
	v_addc_co_u32_e32 v101, vcc, 0, v231, vcc
	global_load_dwordx4 v[100:103], v[100:101], off nt
	s_nop 0
	v_mul_f32_e32 v224, s100, v172
	s_waitcnt vmcnt(25)
	v_add_co_u32_e32 v104, vcc, s71, v230
	v_addc_co_u32_e32 v105, vcc, 0, v231, vcc
	global_load_dwordx4 v[104:107], v[104:105], off nt
	s_nop 0
	v_mul_f32_e32 v148, s100, v176
	v_cvt_pk_fp8_f32 v213, v224, v148 op_sel:[0,0,1]
	s_waitcnt vmcnt(25)
	v_add_co_u32_e32 v108, vcc, s72, v230
	v_addc_co_u32_e32 v109, vcc, 0, v231, vcc
	global_load_dwordx4 v[108:111], v[108:109], off nt
	s_nop 0
	v_mul_f32_e32 v224, s100, v180
	s_waitcnt vmcnt(25)
	v_add_co_u32_e32 v112, vcc, s73, v230
	v_addc_co_u32_e32 v113, vcc, 0, v231, vcc
	global_load_dwordx4 v[112:115], v[112:113], off nt
	s_nop 0
	v_mul_f32_e32 v148, s100, v184
	v_cvt_pk_fp8_f32 v214, v224, v148
	s_waitcnt vmcnt(25)
	v_add_co_u32_e32 v116, vcc, s74, v230
	v_addc_co_u32_e32 v117, vcc, 0, v231, vcc
	global_load_dwordx4 v[116:119], v[116:117], off nt
	s_nop 0
	v_mul_f32_e32 v152, s100, v188
	s_waitcnt vmcnt(25)
	v_add_co_u32_e32 v120, vcc, s75, v230
	v_addc_co_u32_e32 v121, vcc, 0, v231, vcc
	global_load_dwordx4 v[120:123], v[120:121], off nt
	s_nop 0
	v_mul_f32_e32 v156, s100, v192
	s_waitcnt vmcnt(25)
	v_add_co_u32_e32 v124, vcc, s76, v230
	v_addc_co_u32_e32 v125, vcc, 0, v231, vcc
	global_load_dwordx4 v[124:127], v[124:125], off nt
	s_nop 0
	v_mul_f32_e32 v224, s100, v196
	v_cvt_pk_fp8_f32 v214, v152, v156 op_sel:[0,0,1]
	v_mul_f32_e32 v152, s100, v161
	s_waitcnt vmcnt(25)
	v_add_co_u32_e32 v128, vcc, s77, v230
	v_addc_co_u32_e32 v129, vcc, 0, v231, vcc
	global_load_dwordx4 v[128:131], v[128:129], off nt
	s_nop 0
	v_mul_f32_e32 v148, s100, v200
	v_cvt_pk_fp8_f32 v215, v224, v148
	s_waitcnt vmcnt(25)
	v_add_co_u32_e32 v132, vcc, s78, v230
	v_addc_co_u32_e32 v133, vcc, 0, v231, vcc
	global_load_dwordx4 v[132:135], v[132:133], off nt
	s_nop 0
	v_mul_f32_e32 v224, s100, v204
	s_waitcnt vmcnt(25)
	v_mul_f32_e32 v148, s100, v208
	v_cvt_pk_fp8_f32 v215, v224, v148 op_sel:[0,0,1]
	v_mul_f32_e32 v224, s100, v149
	v_mul_f32_e32 v148, s100, v153
	v_cvt_pk_fp8_f32 v216, v224, v148
	v_mul_f32_e32 v224, s100, v165
	v_mul_f32_e32 v148, s100, v169
	v_cvt_pk_fp8_f32 v217, v224, v148
	v_mul_f32_e32 v224, s100, v173
	v_mul_f32_e32 v148, s100, v177
	v_mul_f32_e32 v149, s100, v157
	v_cvt_pk_fp8_f32 v217, v224, v148 op_sel:[0,0,1]
	v_mul_f32_e32 v224, s100, v181
	v_mul_f32_e32 v148, s100, v185
	v_cvt_pk_fp8_f32 v218, v224, v148
	v_mul_f32_e32 v224, s100, v197
	v_mul_f32_e32 v148, s100, v201
	v_cvt_pk_fp8_f32 v219, v224, v148
	v_mul_f32_e32 v224, s100, v205
	v_mul_f32_e32 v148, s100, v209
	v_cvt_pk_fp8_f32 v216, v149, v152 op_sel:[0,0,1]
	v_cvt_pk_fp8_f32 v219, v224, v148 op_sel:[0,0,1]
	v_mul_f32_e32 v224, s100, v150
	v_mul_f32_e32 v148, s100, v154
	v_cvt_pk_fp8_f32 v220, v224, v148
	v_mul_f32_e32 v224, s100, v166
	v_mul_f32_e32 v148, s100, v170
	v_cvt_pk_fp8_f32 v221, v224, v148
	v_mul_f32_e32 v224, s100, v174
	v_mul_f32_e32 v148, s100, v178
	v_mul_f32_e32 v149, s100, v189
	v_cvt_pk_fp8_f32 v221, v224, v148 op_sel:[0,0,1]
	v_mul_f32_e32 v224, s100, v182
	v_mul_f32_e32 v148, s100, v186
	v_cvt_pk_fp8_f32 v222, v224, v148
	v_mul_f32_e32 v224, s100, v198
	v_mul_f32_e32 v148, s100, v202
	v_cvt_pk_fp8_f32 v223, v224, v148
	v_mul_f32_e32 v152, s100, v193
	v_cvt_pk_fp8_f32 v218, v149, v152 op_sel:[0,0,1]
	v_mul_f32_e32 v149, s100, v158
	v_mul_f32_e32 v150, s100, v162
	v_cvt_pk_fp8_f32 v220, v149, v150 op_sel:[0,0,1]
	v_mul_f32_e32 v149, s100, v190
	v_mul_f32_e32 v150, s100, v194
	v_mul_f32_e32 v224, s100, v206
	v_mul_f32_e32 v148, s100, v210
	v_cvt_pk_fp8_f32 v222, v149, v150 op_sel:[0,0,1]
	v_cvt_pk_fp8_f32 v223, v224, v148 op_sel:[0,0,1]
	v_mul_f32_e32 v224, s100, v151
	v_mul_f32_e32 v149, s100, v155
	v_mov_b32_e32 v148, v23
	v_cvt_pk_fp8_f32 v148, v224, v149
	v_mul_f32_e32 v224, s100, v167
	v_mul_f32_e32 v152, s100, v171
	v_mov_b32_e32 v149, v23
	v_cvt_pk_fp8_f32 v149, v224, v152
	v_mul_f32_e32 v150, s100, v159
	v_mul_f32_e32 v151, s100, v163
	v_cvt_pk_fp8_f32 v148, v150, v151 op_sel:[0,0,1]
	v_mul_f32_e32 v224, s100, v175
	v_mul_f32_e32 v150, s100, v179
	v_cvt_pk_fp8_f32 v149, v224, v150 op_sel:[0,0,1]
	v_mul_f32_e32 v224, s100, v183
	v_mul_f32_e32 v151, s100, v187
	v_mov_b32_e32 v150, v23
	v_cvt_pk_fp8_f32 v150, v224, v151
	v_mul_f32_e32 v224, s100, v199
	v_mul_f32_e32 v154, s100, v203
	v_mov_b32_e32 v151, v23
	v_cvt_pk_fp8_f32 v151, v224, v154
	v_mul_f32_e32 v152, s100, v191
	v_mul_f32_e32 v153, s100, v195
	v_cvt_pk_fp8_f32 v150, v152, v153 op_sel:[0,0,1]
	v_mul_f32_e32 v224, s100, v207
	v_mul_f32_e32 v152, s100, v211
	v_cvt_pk_fp8_f32 v151, v224, v152 op_sel:[0,0,1]
	global_store_dwordx4 v[228:229], v[212:215], off
	global_store_dwordx4 v[228:229], v[216:219], off offset:16
	global_store_dwordx4 v[228:229], v[220:223], off offset:32
	global_store_dwordx4 v[228:229], v[148:151], off offset:48
	s_mov_b32 s99, 3
	s_waitcnt vmcnt(20)
	s_andn2_b32 s20, 1, s84
	s_mul_i32 s20, s20, 0xa800
	s_add_i32 s20, s20, 0
	v_add3_u32 v22, s20, v61, v62
	ds_write_b128 v22, v[0:3]
	v_add3_u32 v22, s20, v63, v64
	ds_write_b128 v22, v[4:7]
	v_add3_u32 v22, s20, v65, v66
	ds_write_b128 v22, v[8:11]
	v_add_u32_e32 v22, s20, v20
	v_add3_u32 v48, v22, v67, s63
	v_add3_u32 v22, v22, v68, s63
	ds_write2_b64 v48, v[12:13], v[14:15] offset1:1
	ds_write2_b64 v22, v[16:17], v[18:19] offset1:1
	s_branch .LBB0_1160
.Lp5_st4c:
	s_waitcnt vmcnt(24)
	v_mul_f32_e32 v224, s100, v148
	s_waitcnt vmcnt(23)
	v_mul_f32_e32 v148, s100, v152
	v_cvt_pk_fp8_f32 v212, v224, v148
	s_waitcnt vmcnt(22)
	v_mul_f32_e32 v152, s100, v156
	s_waitcnt vmcnt(21)
	v_mul_f32_e32 v156, s100, v160
	s_waitcnt vmcnt(20)
	v_mul_f32_e32 v224, s100, v164
	v_cvt_pk_fp8_f32 v212, v152, v156 op_sel:[0,0,1]
	s_waitcnt vmcnt(19)
	v_mul_f32_e32 v148, s100, v168
	v_cvt_pk_fp8_f32 v213, v224, v148
	s_waitcnt vmcnt(18)
	v_mul_f32_e32 v224, s100, v172
	s_waitcnt vmcnt(17)
	v_mul_f32_e32 v148, s100, v176
	v_cvt_pk_fp8_f32 v213, v224, v148 op_sel:[0,0,1]
	s_waitcnt vmcnt(16)
	v_mul_f32_e32 v224, s100, v180
	s_waitcnt vmcnt(15)
	v_mul_f32_e32 v148, s100, v184
	v_cvt_pk_fp8_f32 v214, v224, v148
	s_waitcnt vmcnt(14)
	v_mul_f32_e32 v152, s100, v188
	s_waitcnt vmcnt(13)
	v_mul_f32_e32 v156, s100, v192
	s_waitcnt vmcnt(12)
	v_mul_f32_e32 v224, s100, v196
	v_cvt_pk_fp8_f32 v214, v152, v156 op_sel:[0,0,1]
	v_mul_f32_e32 v152, s100, v161
	s_waitcnt vmcnt(11)
	v_mul_f32_e32 v148, s100, v200
	v_cvt_pk_fp8_f32 v215, v224, v148
	s_waitcnt vmcnt(10)
	v_mul_f32_e32 v224, s100, v204
	s_waitcnt vmcnt(9)
	v_mul_f32_e32 v148, s100, v208
	v_cvt_pk_fp8_f32 v215, v224, v148 op_sel:[0,0,1]
	v_mul_f32_e32 v224, s100, v149
	v_mul_f32_e32 v148, s100, v153
	v_cvt_pk_fp8_f32 v216, v224, v148
	v_mul_f32_e32 v224, s100, v165
	v_mul_f32_e32 v148, s100, v169
	v_cvt_pk_fp8_f32 v217, v224, v148
	v_mul_f32_e32 v224, s100, v173
	v_mul_f32_e32 v148, s100, v177
	v_mul_f32_e32 v149, s100, v157
	v_cvt_pk_fp8_f32 v217, v224, v148 op_sel:[0,0,1]
	v_mul_f32_e32 v224, s100, v181
	v_mul_f32_e32 v148, s100, v185
	v_cvt_pk_fp8_f32 v218, v224, v148
	v_mul_f32_e32 v224, s100, v197
	v_mul_f32_e32 v148, s100, v201
	v_cvt_pk_fp8_f32 v219, v224, v148
	v_mul_f32_e32 v224, s100, v205
	v_mul_f32_e32 v148, s100, v209
	v_cvt_pk_fp8_f32 v216, v149, v152 op_sel:[0,0,1]
	v_cvt_pk_fp8_f32 v219, v224, v148 op_sel:[0,0,1]
	v_mul_f32_e32 v224, s100, v150
	v_mul_f32_e32 v148, s100, v154
	v_cvt_pk_fp8_f32 v220, v224, v148
	v_mul_f32_e32 v224, s100, v166
	v_mul_f32_e32 v148, s100, v170
	v_cvt_pk_fp8_f32 v221, v224, v148
	v_mul_f32_e32 v224, s100, v174
	v_mul_f32_e32 v148, s100, v178
	v_mul_f32_e32 v149, s100, v189
	v_cvt_pk_fp8_f32 v221, v224, v148 op_sel:[0,0,1]
	v_mul_f32_e32 v224, s100, v182
	v_mul_f32_e32 v148, s100, v186
	v_cvt_pk_fp8_f32 v222, v224, v148
	v_mul_f32_e32 v224, s100, v198
	v_mul_f32_e32 v148, s100, v202
	v_cvt_pk_fp8_f32 v223, v224, v148
	v_mul_f32_e32 v152, s100, v193
	v_cvt_pk_fp8_f32 v218, v149, v152 op_sel:[0,0,1]
	v_mul_f32_e32 v149, s100, v158
	v_mul_f32_e32 v150, s100, v162
	v_cvt_pk_fp8_f32 v220, v149, v150 op_sel:[0,0,1]
	v_mul_f32_e32 v149, s100, v190
	v_mul_f32_e32 v150, s100, v194
	v_mul_f32_e32 v224, s100, v206
	v_mul_f32_e32 v148, s100, v210
	v_cvt_pk_fp8_f32 v222, v149, v150 op_sel:[0,0,1]
	v_cvt_pk_fp8_f32 v223, v224, v148 op_sel:[0,0,1]
	v_mul_f32_e32 v224, s100, v151
	v_mul_f32_e32 v149, s100, v155
	v_mov_b32_e32 v148, v23
	v_cvt_pk_fp8_f32 v148, v224, v149
	v_mul_f32_e32 v224, s100, v167
	v_mul_f32_e32 v152, s100, v171
	v_mov_b32_e32 v149, v23
	v_cvt_pk_fp8_f32 v149, v224, v152
	v_mul_f32_e32 v150, s100, v159
	v_mul_f32_e32 v151, s100, v163
	v_cvt_pk_fp8_f32 v148, v150, v151 op_sel:[0,0,1]
	v_mul_f32_e32 v224, s100, v175
	v_mul_f32_e32 v150, s100, v179
	v_cvt_pk_fp8_f32 v149, v224, v150 op_sel:[0,0,1]
	v_mul_f32_e32 v224, s100, v183
	v_mul_f32_e32 v151, s100, v187
	v_mov_b32_e32 v150, v23
	v_cvt_pk_fp8_f32 v150, v224, v151
	v_mul_f32_e32 v224, s100, v199
	v_mul_f32_e32 v154, s100, v203
	v_mov_b32_e32 v151, v23
	v_cvt_pk_fp8_f32 v151, v224, v154
	v_mul_f32_e32 v152, s100, v191
	v_mul_f32_e32 v153, s100, v195
	v_cvt_pk_fp8_f32 v150, v152, v153 op_sel:[0,0,1]
	v_mul_f32_e32 v224, s100, v207
	v_mul_f32_e32 v152, s100, v211
	v_cvt_pk_fp8_f32 v151, v224, v152 op_sel:[0,0,1]
	global_store_dwordx4 v[228:229], v[212:215], off
	global_store_dwordx4 v[228:229], v[216:219], off offset:16
	global_store_dwordx4 v[228:229], v[220:223], off offset:32
	global_store_dwordx4 v[228:229], v[148:151], off offset:48
	s_mov_b32 s99, 0
	s_waitcnt vmcnt(4)
	s_andn2_b32 s20, 1, s84
	s_mul_i32 s20, s20, 0xa800
	s_add_i32 s20, s20, 0
	v_add3_u32 v22, s20, v61, v62
	ds_write_b128 v22, v[0:3]
	v_add3_u32 v22, s20, v63, v64
	ds_write_b128 v22, v[4:7]
	v_add3_u32 v22, s20, v65, v66
	ds_write_b128 v22, v[8:11]
	v_add_u32_e32 v22, s20, v20
	v_add3_u32 v48, v22, v67, s63
	v_add3_u32 v22, v22, v68, s63
	ds_write2_b64 v48, v[12:13], v[14:15] offset1:1
	ds_write2_b64 v22, v[16:17], v[18:19] offset1:1
	s_branch .LBB0_1160

.LBB0_2372:
	s_add_i32 s63, s64, 1
	s_cmp_lt_i32 s63, s54
	s_cselect_b64 s[16:17], -1, 0
	s_cmp_ge_i32 s63, s54
	s_cbranch_scc1 .LBB0_2378
	s_cmp_lt_i32 s63, s52
	s_cselect_b32 s12, 0, s52
	s_cselect_b32 s18, s51, s53
	s_lshl_b32 s12, s12, 6
	s_sub_i32 s12, s18, s12
	s_add_i32 s18, s55, s12
	v_add_u32_e32 v0, s18, v29
	v_ashrrev_i32_e32 v1, 31, v0
	v_lshlrev_b64 v[0:1], 9, v[0:1]
	s_ashr_i32 s19, s18, 31
	v_lshl_add_u64 v[0:1], v[18:19], 0, v[0:1]
	v_lshl_add_u64 v[4:5], s[18:19], 1, v[20:21]
	global_load_dwordx4 v[0:3], v[0:1], off
	s_nop 0
	global_load_dwordx4 v[4:7], v[4:5], off
	s_cmp_eq_u32 s99, 3
	s_cbranch_scc1 .Lp13_st3
	s_cmp_eq_u32 s99, 4
	s_cbranch_scc1 .Lp13_st4
	s_cmp_eq_u32 s99, 1
	s_cbranch_scc1 .Lp13_st1
	s_cmp_gt_i32 s3, 0x16fff
	s_cbranch_scc1 .LBB0_2375
	s_add_i32 s12, s63, 1
	s_cmp_ge_u32 s12, s54
	s_cbranch_scc1 .LBB0_2375
	s_ashr_i32 s12, s3, 10
	s_mul_hi_i32 s18, s12, 0x55555556
	s_lshr_b32 s19, s18, 31
	s_add_i32 s20, s18, s19
	s_mul_i32 s18, s20, 3
	s_sub_i32 s24, s12, s18
	s_lshl_b32 s12, s3, 8
	s_ashr_i32 s25, s24, 31
	s_and_b32 s12, s12, 0x700
	s_lshl_b64 s[18:19], s[24:25], 3
	s_add_u32 s22, s0, s18
	s_addc_u32 s23, s1, s19
	s_ashr_i32 s21, s20, 31
	v_or_b32_e32 v10, s12, v28
	s_cmp_lg_u32 s24, 2
	s_mov_b64 s[26:27], -1
	s_cbranch_scc0 .Lp13_i1_2381
	v_lshlrev_b32_e32 v226, 1, v10
	s_lshl_b64 s[18:19], s[20:21], 23
	v_and_b32_e32 v226, 0xf00, v226
	v_lshl_or_b32 v227, s24, 7, v35
	s_add_u32 s18, s28, s18
	v_add_u32_e32 v226, v227, v226
	s_addc_u32 s19, s29, s19
	s_mov_b64 s[26:27], 0

.Lp13_i2_2384:
	s_lshl_b64 s[24:25], s[24:25], 2
	s_waitcnt lgkmcnt(0)
	s_add_u32 s12, s22, s24
	s_addc_u32 s23, s23, s25
	s_bfe_u32 s24, s3, 0x70003
	s_lshl_b32 s22, s24, 17
	s_add_u32 s22, s12, s22
	s_addc_u32 s23, s23, 0
	v_lshlrev_b32_e32 v192, 2, v192
	v_lshl_add_u64 v[232:233], s[22:23], 0, v[192:193]
	global_load_dwordx4 v[116:119], v192, s[22:23] nt
	s_nop 0
	v_mov_b32_e32 v180, v11
	v_mov_b32_e32 v181, v11
	v_mov_b32_e32 v182, v11
	v_mov_b32_e32 v183, v11
	v_mov_b32_e32 v184, v11
	v_mov_b32_e32 v185, v11
	v_mov_b32_e32 v186, v11
	v_mov_b32_e32 v187, v11
	v_mov_b32_e32 v188, v11
	v_mov_b32_e32 v189, v11
	v_mov_b32_e32 v190, v11
	v_mov_b32_e32 v191, v11
	s_mul_i32 s12, s20, s24
	v_ashrrev_i32_e32 v229, 31, v228
	v_lshl_add_u64 v[228:229], s[12:13], 0, v[228:229]
	v_lshl_add_u64 v[228:229], v[228:229], 4, s[18:19]
	s_mov_b32 s100, s21
	s_addk_i32 s3, 0x400
	s_waitcnt vmcnt(18)
	v_add_co_u32_e32 v120, vcc, s35, v232
	v_addc_co_u32_e32 v121, vcc, 0, v233, vcc
	global_load_dwordx4 v[120:123], v[120:121], off nt
	s_nop 0
	v_mul_f32_e32 v10, s98, v40
	s_waitcnt vmcnt(18)
	v_add_co_u32_e32 v124, vcc, s36, v232
	v_addc_co_u32_e32 v125, vcc, 0, v233, vcc
	global_load_dwordx4 v[124:127], v[124:125], off nt
	s_nop 0
	v_mul_f32_e32 v39, s98, v44
	v_cvt_pk_fp8_f32 v104, v10, v39
	s_waitcnt vmcnt(18)
	v_add_co_u32_e32 v128, vcc, s37, v232
	v_addc_co_u32_e32 v129, vcc, 0, v233, vcc
	global_load_dwordx4 v[128:131], v[128:129], off nt
	s_nop 0
	v_mul_f32_e32 v40, s98, v48
	s_waitcnt vmcnt(18)
	v_add_co_u32_e32 v132, vcc, s38, v232
	v_addc_co_u32_e32 v133, vcc, 0, v233, vcc
	global_load_dwordx4 v[132:135], v[132:133], off nt
	s_nop 0
	v_mul_f32_e32 v44, s98, v52
	s_waitcnt vmcnt(18)
	v_add_co_u32_e32 v136, vcc, s39, v232
	v_addc_co_u32_e32 v137, vcc, 0, v233, vcc
	global_load_dwordx4 v[136:139], v[136:137], off nt
	s_nop 0
	v_mul_f32_e32 v10, s98, v56
	v_cvt_pk_fp8_f32 v104, v40, v44 op_sel:[0,0,1]
	s_waitcnt vmcnt(18)
	v_add_co_u32_e32 v140, vcc, s40, v232
	v_addc_co_u32_e32 v141, vcc, 0, v233, vcc
	global_load_dwordx4 v[140:143], v[140:141], off nt
	s_nop 0
	v_mul_f32_e32 v39, s98, v60
	v_cvt_pk_fp8_f32 v105, v10, v39
	s_waitcnt vmcnt(18)
	v_add_co_u32_e32 v144, vcc, s41, v232
	v_addc_co_u32_e32 v145, vcc, 0, v233, vcc
	global_load_dwordx4 v[144:147], v[144:145], off nt
	s_nop 0
	v_mul_f32_e32 v10, s98, v64
	s_waitcnt vmcnt(18)
	v_add_co_u32_e32 v148, vcc, s42, v232
	v_addc_co_u32_e32 v149, vcc, 0, v233, vcc
	global_load_dwordx4 v[148:151], v[148:149], off nt
	s_nop 0
	v_mul_f32_e32 v39, s98, v68
	v_cvt_pk_fp8_f32 v105, v10, v39 op_sel:[0,0,1]
	s_waitcnt vmcnt(18)
	v_add_co_u32_e32 v152, vcc, s43, v232
	v_addc_co_u32_e32 v153, vcc, 0, v233, vcc
	global_load_dwordx4 v[152:155], v[152:153], off nt
	s_nop 0
	v_mul_f32_e32 v10, s98, v72
	s_waitcnt vmcnt(18)
	v_add_co_u32_e32 v156, vcc, s44, v232
	v_addc_co_u32_e32 v157, vcc, 0, v233, vcc
	global_load_dwordx4 v[156:159], v[156:157], off nt
	s_nop 0
	v_mul_f32_e32 v39, s98, v76
	v_cvt_pk_fp8_f32 v106, v10, v39
	s_waitcnt vmcnt(18)
	v_add_co_u32_e32 v160, vcc, s45, v232
	v_addc_co_u32_e32 v161, vcc, 0, v233, vcc
	global_load_dwordx4 v[160:163], v[160:161], off nt
	s_nop 0
	v_mul_f32_e32 v40, s98, v80
	s_waitcnt vmcnt(18)
	v_add_co_u32_e32 v164, vcc, s46, v232
	v_addc_co_u32_e32 v165, vcc, 0, v233, vcc
	global_load_dwordx4 v[164:167], v[164:165], off nt
	s_nop 0
	v_mul_f32_e32 v44, s98, v84
	s_waitcnt vmcnt(18)
	v_add_co_u32_e32 v168, vcc, s47, v232
	v_addc_co_u32_e32 v169, vcc, 0, v233, vcc
	global_load_dwordx4 v[168:171], v[168:169], off nt
	s_nop 0
	v_mul_f32_e32 v10, s98, v88
	v_cvt_pk_fp8_f32 v106, v40, v44 op_sel:[0,0,1]
	v_mul_f32_e32 v40, s98, v49
	v_mul_f32_e32 v44, s98, v83
	s_waitcnt vmcnt(18)
	v_add_co_u32_e32 v172, vcc, s48, v232
	v_addc_co_u32_e32 v173, vcc, 0, v233, vcc
	global_load_dwordx4 v[172:175], v[172:173], off nt
	s_nop 0
	v_mul_f32_e32 v39, s98, v92
	v_cvt_pk_fp8_f32 v107, v10, v39
	s_waitcnt vmcnt(18)
	v_add_co_u32_e32 v176, vcc, s49, v232
	v_addc_co_u32_e32 v177, vcc, 0, v233, vcc
	global_load_dwordx4 v[176:179], v[176:177], off nt
	s_nop 0
	v_mul_f32_e32 v10, s98, v96
	s_waitcnt vmcnt(18)
	v_mul_f32_e32 v39, s98, v100
	v_cvt_pk_fp8_f32 v107, v10, v39 op_sel:[0,0,1]
	v_mul_f32_e32 v10, s98, v41
	v_mul_f32_e32 v39, s98, v45
	v_cvt_pk_fp8_f32 v108, v10, v39
	v_mul_f32_e32 v10, s98, v57
	v_mul_f32_e32 v39, s98, v61
	v_cvt_pk_fp8_f32 v109, v10, v39
	v_mul_f32_e32 v10, s98, v65
	v_mul_f32_e32 v39, s98, v69
	v_mul_f32_e32 v41, s98, v53
	v_cvt_pk_fp8_f32 v109, v10, v39 op_sel:[0,0,1]
	v_mul_f32_e32 v10, s98, v73
	v_mul_f32_e32 v39, s98, v77
	v_cvt_pk_fp8_f32 v110, v10, v39
	v_mul_f32_e32 v10, s98, v89
	v_mul_f32_e32 v39, s98, v93
	v_cvt_pk_fp8_f32 v111, v10, v39
	v_mul_f32_e32 v10, s98, v97
	v_mul_f32_e32 v39, s98, v101
	v_cvt_pk_fp8_f32 v108, v40, v41 op_sel:[0,0,1]
	v_cvt_pk_fp8_f32 v111, v10, v39 op_sel:[0,0,1]
	v_mul_f32_e32 v10, s98, v42
	v_mul_f32_e32 v39, s98, v46
	v_cvt_pk_fp8_f32 v112, v10, v39
	v_mul_f32_e32 v10, s98, v58
	v_mul_f32_e32 v39, s98, v62
	v_cvt_pk_fp8_f32 v113, v10, v39
	v_mul_f32_e32 v10, s98, v66
	v_mul_f32_e32 v39, s98, v70
	v_mul_f32_e32 v40, s98, v81
	v_cvt_pk_fp8_f32 v113, v10, v39 op_sel:[0,0,1]
	v_mul_f32_e32 v10, s98, v74
	v_mul_f32_e32 v39, s98, v78
	v_cvt_pk_fp8_f32 v114, v10, v39
	v_mul_f32_e32 v10, s98, v90
	v_mul_f32_e32 v39, s98, v94
	v_cvt_pk_fp8_f32 v115, v10, v39
	v_mul_f32_e32 v41, s98, v85
	v_cvt_pk_fp8_f32 v110, v40, v41 op_sel:[0,0,1]
	v_mul_f32_e32 v40, s98, v50
	v_mul_f32_e32 v41, s98, v54
	v_cvt_pk_fp8_f32 v112, v40, v41 op_sel:[0,0,1]
	v_mul_f32_e32 v40, s98, v82
	v_mul_f32_e32 v41, s98, v86
	v_mul_f32_e32 v10, s98, v98
	v_mul_f32_e32 v39, s98, v102
	v_cvt_pk_fp8_f32 v114, v40, v41 op_sel:[0,0,1]
	v_cvt_pk_fp8_f32 v115, v10, v39 op_sel:[0,0,1]
	v_mul_f32_e32 v10, s98, v43
	v_mul_f32_e32 v39, s98, v47
	v_mov_b32_e32 v40, v11
	v_cvt_pk_fp8_f32 v40, v10, v39
	v_mul_f32_e32 v10, s98, v59
	v_mul_f32_e32 v39, s98, v63
	v_mov_b32_e32 v41, v11
	v_cvt_pk_fp8_f32 v41, v10, v39
	v_mul_f32_e32 v42, s98, v51
	v_mul_f32_e32 v43, s98, v55
	v_mul_f32_e32 v10, s98, v67
	v_mul_f32_e32 v39, s98, v71
	v_cvt_pk_fp8_f32 v40, v42, v43 op_sel:[0,0,1]
	v_cvt_pk_fp8_f32 v41, v10, v39 op_sel:[0,0,1]
	v_mul_f32_e32 v10, s98, v75
	v_mul_f32_e32 v39, s98, v79
	v_mov_b32_e32 v42, v11
	v_cvt_pk_fp8_f32 v42, v10, v39
	v_mul_f32_e32 v10, s98, v91
	v_mul_f32_e32 v39, s98, v95
	v_mov_b32_e32 v43, v11
	v_cvt_pk_fp8_f32 v43, v10, v39
	v_mul_f32_e32 v45, s98, v87
	v_mul_f32_e32 v10, s98, v99
	v_mul_f32_e32 v39, s98, v103
	v_cvt_pk_fp8_f32 v42, v44, v45 op_sel:[0,0,1]
	v_cvt_pk_fp8_f32 v43, v10, v39 op_sel:[0,0,1]
	global_store_dwordx4 v[226:227], v[104:107], off
	global_store_dwordx4 v[226:227], v[108:111], off offset:16
	global_store_dwordx4 v[226:227], v[112:115], off offset:32
	global_store_dwordx4 v[226:227], v[40:43], off offset:48
	s_mov_b32 s99, 4
	s_waitcnt vmcnt(20)
	s_andn2_b32 s12, 1, s64
	s_mulk_i32 s12, 0x4600
	s_add_i32 s12, s12, 0
	v_add_u32_e32 v10, s12, v33
	v_add3_u32 v22, s12, v31, v32
	v_add3_u32 v10, v10, v34, s34
	ds_write_b128 v22, v[0:3]
	ds_write2_b64 v10, v[4:5], v[6:7] offset1:1
	s_branch .LBB0_2376
.Lp13_st1c:
	s_waitcnt vmcnt(17)
	v_mul_f32_e32 v10, s98, v40
	s_waitcnt vmcnt(16)
	v_mul_f32_e32 v39, s98, v44
	v_cvt_pk_fp8_f32 v104, v10, v39
	s_waitcnt vmcnt(15)
	v_mul_f32_e32 v40, s98, v48
	s_waitcnt vmcnt(14)
	v_mul_f32_e32 v44, s98, v52
	s_waitcnt vmcnt(13)
	v_mul_f32_e32 v10, s98, v56
	v_cvt_pk_fp8_f32 v104, v40, v44 op_sel:[0,0,1]
	s_waitcnt vmcnt(12)
	v_mul_f32_e32 v39, s98, v60
	v_cvt_pk_fp8_f32 v105, v10, v39
	s_waitcnt vmcnt(11)
	v_mul_f32_e32 v10, s98, v64
	s_waitcnt vmcnt(10)
	v_mul_f32_e32 v39, s98, v68
	v_cvt_pk_fp8_f32 v105, v10, v39 op_sel:[0,0,1]
	s_waitcnt vmcnt(9)
	v_mul_f32_e32 v10, s98, v72
	s_waitcnt vmcnt(8)
	v_mul_f32_e32 v39, s98, v76
	v_cvt_pk_fp8_f32 v106, v10, v39
	s_waitcnt vmcnt(7)
	v_mul_f32_e32 v40, s98, v80
	s_waitcnt vmcnt(6)
	v_mul_f32_e32 v44, s98, v84
	s_waitcnt vmcnt(5)
	v_mul_f32_e32 v10, s98, v88
	v_cvt_pk_fp8_f32 v106, v40, v44 op_sel:[0,0,1]
	v_mul_f32_e32 v40, s98, v49
	v_mul_f32_e32 v44, s98, v83
	s_waitcnt vmcnt(4)
	v_mul_f32_e32 v39, s98, v92
	v_cvt_pk_fp8_f32 v107, v10, v39
	s_waitcnt vmcnt(3)
	v_mul_f32_e32 v10, s98, v96
	s_waitcnt vmcnt(2)
	v_mul_f32_e32 v39, s98, v100
	v_cvt_pk_fp8_f32 v107, v10, v39 op_sel:[0,0,1]
	v_mul_f32_e32 v10, s98, v41
	v_mul_f32_e32 v39, s98, v45
	v_cvt_pk_fp8_f32 v108, v10, v39
	v_mul_f32_e32 v10, s98, v57
	v_mul_f32_e32 v39, s98, v61
	v_cvt_pk_fp8_f32 v109, v10, v39
	v_mul_f32_e32 v10, s98, v65
	v_mul_f32_e32 v39, s98, v69
	v_mul_f32_e32 v41, s98, v53
	v_cvt_pk_fp8_f32 v109, v10, v39 op_sel:[0,0,1]
	v_mul_f32_e32 v10, s98, v73
	v_mul_f32_e32 v39, s98, v77
	v_cvt_pk_fp8_f32 v110, v10, v39
	v_mul_f32_e32 v10, s98, v89
	v_mul_f32_e32 v39, s98, v93
	v_cvt_pk_fp8_f32 v111, v10, v39
	v_mul_f32_e32 v10, s98, v97
	v_mul_f32_e32 v39, s98, v101
	v_cvt_pk_fp8_f32 v108, v40, v41 op_sel:[0,0,1]
	v_cvt_pk_fp8_f32 v111, v10, v39 op_sel:[0,0,1]
	v_mul_f32_e32 v10, s98, v42
	v_mul_f32_e32 v39, s98, v46
	v_cvt_pk_fp8_f32 v112, v10, v39
	v_mul_f32_e32 v10, s98, v58
	v_mul_f32_e32 v39, s98, v62
	v_cvt_pk_fp8_f32 v113, v10, v39
	v_mul_f32_e32 v10, s98, v66
	v_mul_f32_e32 v39, s98, v70
	v_mul_f32_e32 v40, s98, v81
	v_cvt_pk_fp8_f32 v113, v10, v39 op_sel:[0,0,1]
	v_mul_f32_e32 v10, s98, v74
	v_mul_f32_e32 v39, s98, v78
	v_cvt_pk_fp8_f32 v114, v10, v39
	v_mul_f32_e32 v10, s98, v90
	v_mul_f32_e32 v39, s98, v94
	v_cvt_pk_fp8_f32 v115, v10, v39
	v_mul_f32_e32 v41, s98, v85
	v_cvt_pk_fp8_f32 v110, v40, v41 op_sel:[0,0,1]
	v_mul_f32_e32 v40, s98, v50
	v_mul_f32_e32 v41, s98, v54
	v_cvt_pk_fp8_f32 v112, v40, v41 op_sel:[0,0,1]
	v_mul_f32_e32 v40, s98, v82
	v_mul_f32_e32 v41, s98, v86
	v_mul_f32_e32 v10, s98, v98
	v_mul_f32_e32 v39, s98, v102
	v_cvt_pk_fp8_f32 v114, v40, v41 op_sel:[0,0,1]
	v_cvt_pk_fp8_f32 v115, v10, v39 op_sel:[0,0,1]
	v_mul_f32_e32 v10, s98, v43
	v_mul_f32_e32 v39, s98, v47
	v_mov_b32_e32 v40, v11
	v_cvt_pk_fp8_f32 v40, v10, v39
	v_mul_f32_e32 v10, s98, v59
	v_mul_f32_e32 v39, s98, v63
	v_mov_b32_e32 v41, v11
	v_cvt_pk_fp8_f32 v41, v10, v39
	v_mul_f32_e32 v42, s98, v51
	v_mul_f32_e32 v43, s98, v55
	v_mul_f32_e32 v10, s98, v67
	v_mul_f32_e32 v39, s98, v71
	v_cvt_pk_fp8_f32 v40, v42, v43 op_sel:[0,0,1]
	v_cvt_pk_fp8_f32 v41, v10, v39 op_sel:[0,0,1]
	v_mul_f32_e32 v10, s98, v75
	v_mul_f32_e32 v39, s98, v79
	v_mov_b32_e32 v42, v11
	v_cvt_pk_fp8_f32 v42, v10, v39
	v_mul_f32_e32 v10, s98, v91
	v_mul_f32_e32 v39, s98, v95
	v_mov_b32_e32 v43, v11
	v_cvt_pk_fp8_f32 v43, v10, v39
	v_mul_f32_e32 v45, s98, v87
	v_mul_f32_e32 v10, s98, v99
	v_mul_f32_e32 v39, s98, v103
	v_cvt_pk_fp8_f32 v42, v44, v45 op_sel:[0,0,1]
	v_cvt_pk_fp8_f32 v43, v10, v39 op_sel:[0,0,1]
	global_store_dwordx4 v[226:227], v[104:107], off
	global_store_dwordx4 v[226:227], v[108:111], off offset:16
	global_store_dwordx4 v[226:227], v[112:115], off offset:32
	global_store_dwordx4 v[226:227], v[40:43], off offset:48
	s_mov_b32 s99, 0
	s_waitcnt vmcnt(4)
	s_andn2_b32 s12, 1, s64
	s_mulk_i32 s12, 0x4600
	s_add_i32 s12, s12, 0
	v_add_u32_e32 v10, s12, v33
	v_add3_u32 v22, s12, v31, v32
	v_add3_u32 v10, v10, v34, s34
	ds_write_b128 v22, v[0:3]
	ds_write2_b64 v10, v[4:5], v[6:7] offset1:1
	s_branch .LBB0_2376
.Lp13_st3:
	s_cmp_gt_i32 s3, 0x16fff
	s_cbranch_scc1 .Lp13_st3c
	s_add_i32 s12, s63, 1
	s_cmp_ge_u32 s12, s54
	s_cbranch_scc1 .Lp13_st3c
	v_mov_b32_e32 v193, 0
	s_ashr_i32 s12, s3, 10
	s_mul_hi_i32 s18, s12, 0x55555556
	s_lshr_b32 s19, s18, 31
	s_add_i32 s20, s18, s19
	s_mul_i32 s18, s20, 3
	s_sub_i32 s24, s12, s18
	s_lshl_b32 s12, s3, 8
	s_ashr_i32 s25, s24, 31
	s_and_b32 s12, s12, 0x700
	s_lshl_b64 s[18:19], s[24:25], 3
	s_add_u32 s22, s0, s18
	s_addc_u32 s23, s1, s19
	s_ashr_i32 s21, s20, 31
	v_or_b32_e32 v192, s12, v28
	s_cmp_lg_u32 s24, 2
	s_mov_b64 s[26:27], -1
	s_cbranch_scc0 .Lp13_i3_2381
	v_lshlrev_b32_e32 v228, 1, v192
	s_lshl_b64 s[18:19], s[20:21], 23
	v_and_b32_e32 v228, 0xf00, v228
	v_lshl_or_b32 v229, s24, 7, v35
	s_add_u32 s18, s28, s18
	v_add_u32_e32 v228, v229, v228
	s_addc_u32 s19, s29, s19
	s_mov_b64 s[26:27], 0

.Lp13_i3_2384:
	s_lshl_b64 s[24:25], s[24:25], 2
	s_waitcnt lgkmcnt(0)
	s_add_u32 s12, s22, s24
	s_addc_u32 s23, s23, s25
	s_bfe_u32 s24, s3, 0x70003
	s_lshl_b32 s22, s24, 17
	s_add_u32 s22, s12, s22
	s_addc_u32 s23, s23, 0
	v_lshlrev_b32_e32 v192, 2, v192
	v_lshl_add_u64 v[232:233], s[22:23], 0, v[192:193]
	global_load_dwordx4 v[116:119], v192, s[22:23] nt
	s_nop 0
	v_mov_b32_e32 v180, v11
	v_mov_b32_e32 v181, v11
	v_mov_b32_e32 v182, v11
	v_mov_b32_e32 v183, v11
	v_mov_b32_e32 v184, v11
	v_mov_b32_e32 v185, v11
	v_mov_b32_e32 v186, v11
	v_mov_b32_e32 v187, v11
	v_mov_b32_e32 v188, v11
	v_mov_b32_e32 v189, v11
	v_mov_b32_e32 v190, v11
	v_mov_b32_e32 v191, v11
	s_mul_i32 s12, s20, s24
	v_ashrrev_i32_e32 v229, 31, v228
	v_lshl_add_u64 v[228:229], s[12:13], 0, v[228:229]
	v_lshl_add_u64 v[228:229], v[228:229], 4, s[18:19]
	s_mov_b32 s100, s21
	s_addk_i32 s3, 0x400
	s_waitcnt vmcnt(22)
	v_add_co_u32_e32 v120, vcc, s35, v232
	v_addc_co_u32_e32 v121, vcc, 0, v233, vcc
	global_load_dwordx4 v[120:123], v[120:121], off nt
	s_nop 0
	v_mul_f32_e32 v10, s98, v40
	s_waitcnt vmcnt(22)
	v_add_co_u32_e32 v124, vcc, s36, v232
	v_addc_co_u32_e32 v125, vcc, 0, v233, vcc
	global_load_dwordx4 v[124:127], v[124:125], off nt
	s_nop 0
	v_mul_f32_e32 v39, s98, v44
	v_cvt_pk_fp8_f32 v104, v10, v39
	s_waitcnt vmcnt(22)
	v_add_co_u32_e32 v128, vcc, s37, v232
	v_addc_co_u32_e32 v129, vcc, 0, v233, vcc
	global_load_dwordx4 v[128:131], v[128:129], off nt
	s_nop 0
	v_mul_f32_e32 v40, s98, v48
	s_waitcnt vmcnt(22)
	v_add_co_u32_e32 v132, vcc, s38, v232
	v_addc_co_u32_e32 v133, vcc, 0, v233, vcc
	global_load_dwordx4 v[132:135], v[132:133], off nt
	s_nop 0
	v_mul_f32_e32 v44, s98, v52
	s_waitcnt vmcnt(22)
	v_add_co_u32_e32 v136, vcc, s39, v232
	v_addc_co_u32_e32 v137, vcc, 0, v233, vcc
	global_load_dwordx4 v[136:139], v[136:137], off nt
	s_nop 0
	v_mul_f32_e32 v10, s98, v56
	v_cvt_pk_fp8_f32 v104, v40, v44 op_sel:[0,0,1]
	s_waitcnt vmcnt(22)
	v_add_co_u32_e32 v140, vcc, s40, v232
	v_addc_co_u32_e32 v141, vcc, 0, v233, vcc
	global_load_dwordx4 v[140:143], v[140:141], off nt
	s_nop 0
	v_mul_f32_e32 v39, s98, v60
	v_cvt_pk_fp8_f32 v105, v10, v39
	s_waitcnt vmcnt(22)
	v_add_co_u32_e32 v144, vcc, s41, v232
	v_addc_co_u32_e32 v145, vcc, 0, v233, vcc
	global_load_dwordx4 v[144:147], v[144:145], off nt
	s_nop 0
	v_mul_f32_e32 v10, s98, v64
	s_waitcnt vmcnt(22)
	v_add_co_u32_e32 v148, vcc, s42, v232
	v_addc_co_u32_e32 v149, vcc, 0, v233, vcc
	global_load_dwordx4 v[148:151], v[148:149], off nt
	s_nop 0
	v_mul_f32_e32 v39, s98, v68
	v_cvt_pk_fp8_f32 v105, v10, v39 op_sel:[0,0,1]
	s_waitcnt vmcnt(22)
	v_add_co_u32_e32 v152, vcc, s43, v232
	v_addc_co_u32_e32 v153, vcc, 0, v233, vcc
	global_load_dwordx4 v[152:155], v[152:153], off nt
	s_nop 0
	v_mul_f32_e32 v10, s98, v72
	s_waitcnt vmcnt(22)
	v_add_co_u32_e32 v156, vcc, s44, v232
	v_addc_co_u32_e32 v157, vcc, 0, v233, vcc
	global_load_dwordx4 v[156:159], v[156:157], off nt
	s_nop 0
	v_mul_f32_e32 v39, s98, v76
	v_cvt_pk_fp8_f32 v106, v10, v39
	s_waitcnt vmcnt(22)
	v_add_co_u32_e32 v160, vcc, s45, v232
	v_addc_co_u32_e32 v161, vcc, 0, v233, vcc
	global_load_dwordx4 v[160:163], v[160:161], off nt
	s_nop 0
	v_mul_f32_e32 v40, s98, v80
	s_waitcnt vmcnt(22)
	v_add_co_u32_e32 v164, vcc, s46, v232
	v_addc_co_u32_e32 v165, vcc, 0, v233, vcc
	global_load_dwordx4 v[164:167], v[164:165], off nt
	s_nop 0
	v_mul_f32_e32 v44, s98, v84
	s_waitcnt vmcnt(22)
	v_add_co_u32_e32 v168, vcc, s47, v232
	v_addc_co_u32_e32 v169, vcc, 0, v233, vcc
	global_load_dwordx4 v[168:171], v[168:169], off nt
	s_nop 0
	v_mul_f32_e32 v10, s98, v88
	v_cvt_pk_fp8_f32 v106, v40, v44 op_sel:[0,0,1]
	v_mul_f32_e32 v40, s98, v49
	v_mul_f32_e32 v44, s98, v83
	s_waitcnt vmcnt(22)
	v_add_co_u32_e32 v172, vcc, s48, v232
	v_addc_co_u32_e32 v173, vcc, 0, v233, vcc
	global_load_dwordx4 v[172:175], v[172:173], off nt
	s_nop 0
	v_mul_f32_e32 v39, s98, v92
	v_cvt_pk_fp8_f32 v107, v10, v39
	s_waitcnt vmcnt(22)
	v_add_co_u32_e32 v176, vcc, s49, v232
	v_addc_co_u32_e32 v177, vcc, 0, v233, vcc
	global_load_dwordx4 v[176:179], v[176:177], off nt
	s_nop 0
	v_mul_f32_e32 v10, s98, v96
	s_waitcnt vmcnt(22)
	v_mul_f32_e32 v39, s98, v100
	v_cvt_pk_fp8_f32 v107, v10, v39 op_sel:[0,0,1]
	v_mul_f32_e32 v10, s98, v41
	v_mul_f32_e32 v39, s98, v45
	v_cvt_pk_fp8_f32 v108, v10, v39
	v_mul_f32_e32 v10, s98, v57
	v_mul_f32_e32 v39, s98, v61
	v_cvt_pk_fp8_f32 v109, v10, v39
	v_mul_f32_e32 v10, s98, v65
	v_mul_f32_e32 v39, s98, v69
	v_mul_f32_e32 v41, s98, v53
	v_cvt_pk_fp8_f32 v109, v10, v39 op_sel:[0,0,1]
	v_mul_f32_e32 v10, s98, v73
	v_mul_f32_e32 v39, s98, v77
	v_cvt_pk_fp8_f32 v110, v10, v39
	v_mul_f32_e32 v10, s98, v89
	v_mul_f32_e32 v39, s98, v93
	v_cvt_pk_fp8_f32 v111, v10, v39
	v_mul_f32_e32 v10, s98, v97
	v_mul_f32_e32 v39, s98, v101
	v_cvt_pk_fp8_f32 v108, v40, v41 op_sel:[0,0,1]
	v_cvt_pk_fp8_f32 v111, v10, v39 op_sel:[0,0,1]
	v_mul_f32_e32 v10, s98, v42
	v_mul_f32_e32 v39, s98, v46
	v_cvt_pk_fp8_f32 v112, v10, v39
	v_mul_f32_e32 v10, s98, v58
	v_mul_f32_e32 v39, s98, v62
	v_cvt_pk_fp8_f32 v113, v10, v39
	v_mul_f32_e32 v10, s98, v66
	v_mul_f32_e32 v39, s98, v70
	v_mul_f32_e32 v40, s98, v81
	v_cvt_pk_fp8_f32 v113, v10, v39 op_sel:[0,0,1]
	v_mul_f32_e32 v10, s98, v74
	v_mul_f32_e32 v39, s98, v78
	v_cvt_pk_fp8_f32 v114, v10, v39
	v_mul_f32_e32 v10, s98, v90
	v_mul_f32_e32 v39, s98, v94
	v_cvt_pk_fp8_f32 v115, v10, v39
	v_mul_f32_e32 v41, s98, v85
	v_cvt_pk_fp8_f32 v110, v40, v41 op_sel:[0,0,1]
	v_mul_f32_e32 v40, s98, v50
	v_mul_f32_e32 v41, s98, v54
	v_cvt_pk_fp8_f32 v112, v40, v41 op_sel:[0,0,1]
	v_mul_f32_e32 v40, s98, v82
	v_mul_f32_e32 v41, s98, v86
	v_mul_f32_e32 v10, s98, v98
	v_mul_f32_e32 v39, s98, v102
	v_cvt_pk_fp8_f32 v114, v40, v41 op_sel:[0,0,1]
	v_cvt_pk_fp8_f32 v115, v10, v39 op_sel:[0,0,1]
	v_mul_f32_e32 v10, s98, v43
	v_mul_f32_e32 v39, s98, v47
	v_mov_b32_e32 v40, v11
	v_cvt_pk_fp8_f32 v40, v10, v39
	v_mul_f32_e32 v10, s98, v59
	v_mul_f32_e32 v39, s98, v63
	v_mov_b32_e32 v41, v11
	v_cvt_pk_fp8_f32 v41, v10, v39
	v_mul_f32_e32 v42, s98, v51
	v_mul_f32_e32 v43, s98, v55
	v_mul_f32_e32 v10, s98, v67
	v_mul_f32_e32 v39, s98, v71
	v_cvt_pk_fp8_f32 v40, v42, v43 op_sel:[0,0,1]
	v_cvt_pk_fp8_f32 v41, v10, v39 op_sel:[0,0,1]
	v_mul_f32_e32 v10, s98, v75
	v_mul_f32_e32 v39, s98, v79
	v_mov_b32_e32 v42, v11
	v_cvt_pk_fp8_f32 v42, v10, v39
	v_mul_f32_e32 v10, s98, v91
	v_mul_f32_e32 v39, s98, v95
	v_mov_b32_e32 v43, v11
	v_cvt_pk_fp8_f32 v43, v10, v39
	v_mul_f32_e32 v45, s98, v87
	v_mul_f32_e32 v10, s98, v99
	v_mul_f32_e32 v39, s98, v103
	v_cvt_pk_fp8_f32 v42, v44, v45 op_sel:[0,0,1]
	v_cvt_pk_fp8_f32 v43, v10, v39 op_sel:[0,0,1]
	global_store_dwordx4 v[226:227], v[104:107], off
	global_store_dwordx4 v[226:227], v[108:111], off offset:16
	global_store_dwordx4 v[226:227], v[112:115], off offset:32
	global_store_dwordx4 v[226:227], v[40:43], off offset:48
	s_mov_b32 s99, 4
	s_waitcnt vmcnt(20)
	s_andn2_b32 s12, 1, s64
	s_mulk_i32 s12, 0x4600
	s_add_i32 s12, s12, 0
	v_add_u32_e32 v10, s12, v33
	v_add3_u32 v22, s12, v31, v32
	v_add3_u32 v10, v10, v34, s34
	ds_write_b128 v22, v[0:3]
	ds_write2_b64 v10, v[4:5], v[6:7] offset1:1
	s_branch .LBB0_2376
.Lp13_st3c:
	s_waitcnt vmcnt(21)
	v_mul_f32_e32 v10, s98, v40
	s_waitcnt vmcnt(20)
	v_mul_f32_e32 v39, s98, v44
	v_cvt_pk_fp8_f32 v104, v10, v39
	s_waitcnt vmcnt(19)
	v_mul_f32_e32 v40, s98, v48
	s_waitcnt vmcnt(18)
	v_mul_f32_e32 v44, s98, v52
	s_waitcnt vmcnt(17)
	v_mul_f32_e32 v10, s98, v56
	v_cvt_pk_fp8_f32 v104, v40, v44 op_sel:[0,0,1]
	s_waitcnt vmcnt(16)
	v_mul_f32_e32 v39, s98, v60
	v_cvt_pk_fp8_f32 v105, v10, v39
	s_waitcnt vmcnt(15)
	v_mul_f32_e32 v10, s98, v64
	s_waitcnt vmcnt(14)
	v_mul_f32_e32 v39, s98, v68
	v_cvt_pk_fp8_f32 v105, v10, v39 op_sel:[0,0,1]
	s_waitcnt vmcnt(13)
	v_mul_f32_e32 v10, s98, v72
	s_waitcnt vmcnt(12)
	v_mul_f32_e32 v39, s98, v76
	v_cvt_pk_fp8_f32 v106, v10, v39
	s_waitcnt vmcnt(11)
	v_mul_f32_e32 v40, s98, v80
	s_waitcnt vmcnt(10)
	v_mul_f32_e32 v44, s98, v84
	s_waitcnt vmcnt(9)
	v_mul_f32_e32 v10, s98, v88
	v_cvt_pk_fp8_f32 v106, v40, v44 op_sel:[0,0,1]
	v_mul_f32_e32 v40, s98, v49
	v_mul_f32_e32 v44, s98, v83
	s_waitcnt vmcnt(8)
	v_mul_f32_e32 v39, s98, v92
	v_cvt_pk_fp8_f32 v107, v10, v39
	s_waitcnt vmcnt(7)
	v_mul_f32_e32 v10, s98, v96
	s_waitcnt vmcnt(6)
	v_mul_f32_e32 v39, s98, v100
	v_cvt_pk_fp8_f32 v107, v10, v39 op_sel:[0,0,1]
	v_mul_f32_e32 v10, s98, v41
	v_mul_f32_e32 v39, s98, v45
	v_cvt_pk_fp8_f32 v108, v10, v39
	v_mul_f32_e32 v10, s98, v57
	v_mul_f32_e32 v39, s98, v61
	v_cvt_pk_fp8_f32 v109, v10, v39
	v_mul_f32_e32 v10, s98, v65
	v_mul_f32_e32 v39, s98, v69
	v_mul_f32_e32 v41, s98, v53
	v_cvt_pk_fp8_f32 v109, v10, v39 op_sel:[0,0,1]
	v_mul_f32_e32 v10, s98, v73
	v_mul_f32_e32 v39, s98, v77
	v_cvt_pk_fp8_f32 v110, v10, v39
	v_mul_f32_e32 v10, s98, v89
	v_mul_f32_e32 v39, s98, v93
	v_cvt_pk_fp8_f32 v111, v10, v39
	v_mul_f32_e32 v10, s98, v97
	v_mul_f32_e32 v39, s98, v101
	v_cvt_pk_fp8_f32 v108, v40, v41 op_sel:[0,0,1]
	v_cvt_pk_fp8_f32 v111, v10, v39 op_sel:[0,0,1]
	v_mul_f32_e32 v10, s98, v42
	v_mul_f32_e32 v39, s98, v46
	v_cvt_pk_fp8_f32 v112, v10, v39
	v_mul_f32_e32 v10, s98, v58
	v_mul_f32_e32 v39, s98, v62
	v_cvt_pk_fp8_f32 v113, v10, v39
	v_mul_f32_e32 v10, s98, v66
	v_mul_f32_e32 v39, s98, v70
	v_mul_f32_e32 v40, s98, v81
	v_cvt_pk_fp8_f32 v113, v10, v39 op_sel:[0,0,1]
	v_mul_f32_e32 v10, s98, v74
	v_mul_f32_e32 v39, s98, v78
	v_cvt_pk_fp8_f32 v114, v10, v39
	v_mul_f32_e32 v10, s98, v90
	v_mul_f32_e32 v39, s98, v94
	v_cvt_pk_fp8_f32 v115, v10, v39
	v_mul_f32_e32 v41, s98, v85
	v_cvt_pk_fp8_f32 v110, v40, v41 op_sel:[0,0,1]
	v_mul_f32_e32 v40, s98, v50
	v_mul_f32_e32 v41, s98, v54
	v_cvt_pk_fp8_f32 v112, v40, v41 op_sel:[0,0,1]
	v_mul_f32_e32 v40, s98, v82
	v_mul_f32_e32 v41, s98, v86
	v_mul_f32_e32 v10, s98, v98
	v_mul_f32_e32 v39, s98, v102
	v_cvt_pk_fp8_f32 v114, v40, v41 op_sel:[0,0,1]
	v_cvt_pk_fp8_f32 v115, v10, v39 op_sel:[0,0,1]
	v_mul_f32_e32 v10, s98, v43
	v_mul_f32_e32 v39, s98, v47
	v_mov_b32_e32 v40, v11
	v_cvt_pk_fp8_f32 v40, v10, v39
	v_mul_f32_e32 v10, s98, v59
	v_mul_f32_e32 v39, s98, v63
	v_mov_b32_e32 v41, v11
	v_cvt_pk_fp8_f32 v41, v10, v39
	v_mul_f32_e32 v42, s98, v51
	v_mul_f32_e32 v43, s98, v55
	v_mul_f32_e32 v10, s98, v67
	v_mul_f32_e32 v39, s98, v71
	v_cvt_pk_fp8_f32 v40, v42, v43 op_sel:[0,0,1]
	v_cvt_pk_fp8_f32 v41, v10, v39 op_sel:[0,0,1]
	v_mul_f32_e32 v10, s98, v75
	v_mul_f32_e32 v39, s98, v79
	v_mov_b32_e32 v42, v11
	v_cvt_pk_fp8_f32 v42, v10, v39
	v_mul_f32_e32 v10, s98, v91
	v_mul_f32_e32 v39, s98, v95
	v_mov_b32_e32 v43, v11
	v_cvt_pk_fp8_f32 v43, v10, v39
	v_mul_f32_e32 v45, s98, v87
	v_mul_f32_e32 v10, s98, v99
	v_mul_f32_e32 v39, s98, v103
	v_cvt_pk_fp8_f32 v42, v44, v45 op_sel:[0,0,1]
	v_cvt_pk_fp8_f32 v43, v10, v39 op_sel:[0,0,1]
	global_store_dwordx4 v[226:227], v[104:107], off
	global_store_dwordx4 v[226:227], v[108:111], off offset:16
	global_store_dwordx4 v[226:227], v[112:115], off offset:32
	global_store_dwordx4 v[226:227], v[40:43], off offset:48
	s_mov_b32 s99, 0
	s_waitcnt vmcnt(4)
	s_andn2_b32 s12, 1, s64
	s_mulk_i32 s12, 0x4600
	s_add_i32 s12, s12, 0
	v_add_u32_e32 v10, s12, v33
	v_add3_u32 v22, s12, v31, v32
	v_add3_u32 v10, v10, v34, s34
	ds_write_b128 v22, v[0:3]
	ds_write2_b64 v10, v[4:5], v[6:7] offset1:1
	s_branch .LBB0_2376

.Lp13_i4_2384:
	s_lshl_b64 s[24:25], s[24:25], 2
	s_waitcnt lgkmcnt(0)
	s_add_u32 s12, s22, s24
	s_addc_u32 s23, s23, s25
	s_bfe_u32 s24, s3, 0x70003
	s_lshl_b32 s22, s24, 17
	s_add_u32 s22, s12, s22
	s_addc_u32 s23, s23, 0
	v_lshlrev_b32_e32 v10, 2, v10
	v_lshl_add_u64 v[230:231], s[22:23], 0, v[10:11]
	global_load_dwordx4 v[40:43], v10, s[22:23] nt
	s_nop 0
	v_mov_b32_e32 v104, v11
	v_mov_b32_e32 v105, v11
	v_mov_b32_e32 v106, v11
	v_mov_b32_e32 v107, v11
	v_mov_b32_e32 v108, v11
	v_mov_b32_e32 v109, v11
	v_mov_b32_e32 v110, v11
	v_mov_b32_e32 v111, v11
	v_mov_b32_e32 v112, v11
	v_mov_b32_e32 v113, v11
	v_mov_b32_e32 v114, v11
	v_mov_b32_e32 v115, v11
	s_mul_i32 s12, s20, s24
	v_ashrrev_i32_e32 v227, 31, v226
	v_lshl_add_u64 v[226:227], s[12:13], 0, v[226:227]
	v_lshl_add_u64 v[226:227], v[226:227], 4, s[18:19]
	s_mov_b32 s98, s21
	s_addk_i32 s3, 0x400
	s_waitcnt vmcnt(22)
	v_add_co_u32_e32 v44, vcc, s35, v230
	v_addc_co_u32_e32 v45, vcc, 0, v231, vcc
	global_load_dwordx4 v[44:47], v[44:45], off nt
	s_nop 0
	v_mul_f32_e32 v192, s100, v116
	s_waitcnt vmcnt(22)
	v_add_co_u32_e32 v48, vcc, s36, v230
	v_addc_co_u32_e32 v49, vcc, 0, v231, vcc
	global_load_dwordx4 v[48:51], v[48:49], off nt
	s_nop 0
	v_mul_f32_e32 v196, s100, v120
	v_cvt_pk_fp8_f32 v180, v192, v196
	s_waitcnt vmcnt(22)
	v_add_co_u32_e32 v52, vcc, s37, v230
	v_addc_co_u32_e32 v53, vcc, 0, v231, vcc
	global_load_dwordx4 v[52:55], v[52:53], off nt
	s_nop 0
	v_mul_f32_e32 v116, s100, v124
	s_waitcnt vmcnt(22)
	v_add_co_u32_e32 v56, vcc, s38, v230
	v_addc_co_u32_e32 v57, vcc, 0, v231, vcc
	global_load_dwordx4 v[56:59], v[56:57], off nt
	s_nop 0
	v_mul_f32_e32 v120, s100, v128
	s_waitcnt vmcnt(22)
	v_add_co_u32_e32 v60, vcc, s39, v230
	v_addc_co_u32_e32 v61, vcc, 0, v231, vcc
	global_load_dwordx4 v[60:63], v[60:61], off nt
	s_nop 0
	v_mul_f32_e32 v192, s100, v132
	v_cvt_pk_fp8_f32 v180, v116, v120 op_sel:[0,0,1]
	s_waitcnt vmcnt(22)
	v_add_co_u32_e32 v64, vcc, s40, v230
	v_addc_co_u32_e32 v65, vcc, 0, v231, vcc
	global_load_dwordx4 v[64:67], v[64:65], off nt
	s_nop 0
	v_mul_f32_e32 v196, s100, v136
	v_cvt_pk_fp8_f32 v181, v192, v196
	s_waitcnt vmcnt(22)
	v_add_co_u32_e32 v68, vcc, s41, v230
	v_addc_co_u32_e32 v69, vcc, 0, v231, vcc
	global_load_dwordx4 v[68:71], v[68:69], off nt
	s_nop 0
	v_mul_f32_e32 v192, s100, v140
	s_waitcnt vmcnt(22)
	v_add_co_u32_e32 v72, vcc, s42, v230
	v_addc_co_u32_e32 v73, vcc, 0, v231, vcc
	global_load_dwordx4 v[72:75], v[72:73], off nt
	s_nop 0
	v_mul_f32_e32 v196, s100, v144
	v_cvt_pk_fp8_f32 v181, v192, v196 op_sel:[0,0,1]
	s_waitcnt vmcnt(22)
	v_add_co_u32_e32 v76, vcc, s43, v230
	v_addc_co_u32_e32 v77, vcc, 0, v231, vcc
	global_load_dwordx4 v[76:79], v[76:77], off nt
	s_nop 0
	v_mul_f32_e32 v192, s100, v148
	s_waitcnt vmcnt(22)
	v_add_co_u32_e32 v80, vcc, s44, v230
	v_addc_co_u32_e32 v81, vcc, 0, v231, vcc
	global_load_dwordx4 v[80:83], v[80:81], off nt
	s_nop 0
	v_mul_f32_e32 v196, s100, v152
	v_cvt_pk_fp8_f32 v182, v192, v196
	s_waitcnt vmcnt(22)
	v_add_co_u32_e32 v84, vcc, s45, v230
	v_addc_co_u32_e32 v85, vcc, 0, v231, vcc
	global_load_dwordx4 v[84:87], v[84:85], off nt
	s_nop 0
	v_mul_f32_e32 v116, s100, v156
	s_waitcnt vmcnt(22)
	v_add_co_u32_e32 v88, vcc, s46, v230
	v_addc_co_u32_e32 v89, vcc, 0, v231, vcc
	global_load_dwordx4 v[88:91], v[88:89], off nt
	s_nop 0
	v_mul_f32_e32 v120, s100, v160
	s_waitcnt vmcnt(22)
	v_add_co_u32_e32 v92, vcc, s47, v230
	v_addc_co_u32_e32 v93, vcc, 0, v231, vcc
	global_load_dwordx4 v[92:95], v[92:93], off nt
	s_nop 0
	v_mul_f32_e32 v192, s100, v164
	v_cvt_pk_fp8_f32 v182, v116, v120 op_sel:[0,0,1]
	v_mul_f32_e32 v116, s100, v125
	v_mul_f32_e32 v120, s100, v159
	s_waitcnt vmcnt(22)
	v_add_co_u32_e32 v96, vcc, s48, v230
	v_addc_co_u32_e32 v97, vcc, 0, v231, vcc
	global_load_dwordx4 v[96:99], v[96:97], off nt
	s_nop 0
	v_mul_f32_e32 v196, s100, v168
	v_cvt_pk_fp8_f32 v183, v192, v196
	s_waitcnt vmcnt(22)
	v_add_co_u32_e32 v100, vcc, s49, v230
	v_addc_co_u32_e32 v101, vcc, 0, v231, vcc
	global_load_dwordx4 v[100:103], v[100:101], off nt
	s_nop 0
	v_mul_f32_e32 v192, s100, v172
	s_waitcnt vmcnt(22)
	v_mul_f32_e32 v196, s100, v176
	v_cvt_pk_fp8_f32 v183, v192, v196 op_sel:[0,0,1]
	v_mul_f32_e32 v192, s100, v117
	v_mul_f32_e32 v196, s100, v121
	v_cvt_pk_fp8_f32 v184, v192, v196
	v_mul_f32_e32 v192, s100, v133
	v_mul_f32_e32 v196, s100, v137
	v_cvt_pk_fp8_f32 v185, v192, v196
	v_mul_f32_e32 v192, s100, v141
	v_mul_f32_e32 v196, s100, v145
	v_mul_f32_e32 v117, s100, v129
	v_cvt_pk_fp8_f32 v185, v192, v196 op_sel:[0,0,1]
	v_mul_f32_e32 v192, s100, v149
	v_mul_f32_e32 v196, s100, v153
	v_cvt_pk_fp8_f32 v186, v192, v196
	v_mul_f32_e32 v192, s100, v165
	v_mul_f32_e32 v196, s100, v169
	v_cvt_pk_fp8_f32 v187, v192, v196
	v_mul_f32_e32 v192, s100, v173
	v_mul_f32_e32 v196, s100, v177
	v_cvt_pk_fp8_f32 v184, v116, v117 op_sel:[0,0,1]
	v_cvt_pk_fp8_f32 v187, v192, v196 op_sel:[0,0,1]
	v_mul_f32_e32 v192, s100, v118
	v_mul_f32_e32 v196, s100, v122
	v_cvt_pk_fp8_f32 v188, v192, v196
	v_mul_f32_e32 v192, s100, v134
	v_mul_f32_e32 v196, s100, v138
	v_cvt_pk_fp8_f32 v189, v192, v196
	v_mul_f32_e32 v192, s100, v142
	v_mul_f32_e32 v196, s100, v146
	v_mul_f32_e32 v116, s100, v157
	v_cvt_pk_fp8_f32 v189, v192, v196 op_sel:[0,0,1]
	v_mul_f32_e32 v192, s100, v150
	v_mul_f32_e32 v196, s100, v154
	v_cvt_pk_fp8_f32 v190, v192, v196
	v_mul_f32_e32 v192, s100, v166
	v_mul_f32_e32 v196, s100, v170
	v_cvt_pk_fp8_f32 v191, v192, v196
	v_mul_f32_e32 v117, s100, v161
	v_cvt_pk_fp8_f32 v186, v116, v117 op_sel:[0,0,1]
	v_mul_f32_e32 v116, s100, v126
	v_mul_f32_e32 v117, s100, v130
	v_cvt_pk_fp8_f32 v188, v116, v117 op_sel:[0,0,1]
	v_mul_f32_e32 v116, s100, v158
	v_mul_f32_e32 v117, s100, v162
	v_mul_f32_e32 v192, s100, v174
	v_mul_f32_e32 v196, s100, v178
	v_cvt_pk_fp8_f32 v190, v116, v117 op_sel:[0,0,1]
	v_cvt_pk_fp8_f32 v191, v192, v196 op_sel:[0,0,1]
	v_mul_f32_e32 v192, s100, v119
	v_mul_f32_e32 v196, s100, v123
	v_mov_b32_e32 v116, v11
	v_cvt_pk_fp8_f32 v116, v192, v196
	v_mul_f32_e32 v192, s100, v135
	v_mul_f32_e32 v196, s100, v139
	v_mov_b32_e32 v117, v11
	v_cvt_pk_fp8_f32 v117, v192, v196
	v_mul_f32_e32 v118, s100, v127
	v_mul_f32_e32 v119, s100, v131
	v_mul_f32_e32 v192, s100, v143
	v_mul_f32_e32 v196, s100, v147
	v_cvt_pk_fp8_f32 v116, v118, v119 op_sel:[0,0,1]
	v_cvt_pk_fp8_f32 v117, v192, v196 op_sel:[0,0,1]
	v_mul_f32_e32 v192, s100, v151
	v_mul_f32_e32 v196, s100, v155
	v_mov_b32_e32 v118, v11
	v_cvt_pk_fp8_f32 v118, v192, v196
	v_mul_f32_e32 v192, s100, v167
	v_mul_f32_e32 v196, s100, v171
	v_mov_b32_e32 v119, v11
	v_cvt_pk_fp8_f32 v119, v192, v196
	v_mul_f32_e32 v121, s100, v163
	v_mul_f32_e32 v192, s100, v175
	v_mul_f32_e32 v196, s100, v179
	v_cvt_pk_fp8_f32 v118, v120, v121 op_sel:[0,0,1]
	v_cvt_pk_fp8_f32 v119, v192, v196 op_sel:[0,0,1]
	global_store_dwordx4 v[228:229], v[180:183], off
	global_store_dwordx4 v[228:229], v[184:187], off offset:16
	global_store_dwordx4 v[228:229], v[188:191], off offset:32
	global_store_dwordx4 v[228:229], v[116:119], off offset:48
	s_mov_b32 s99, 3
	s_waitcnt vmcnt(20)
	s_andn2_b32 s12, 1, s64
	s_mulk_i32 s12, 0x4600
	s_add_i32 s12, s12, 0
	v_add_u32_e32 v10, s12, v33
	v_add3_u32 v22, s12, v31, v32
	v_add3_u32 v10, v10, v34, s34
	ds_write_b128 v22, v[0:3]
	ds_write2_b64 v10, v[4:5], v[6:7] offset1:1
	s_branch .LBB0_2376
.Lp13_st4c:
	s_waitcnt vmcnt(21)
	v_mul_f32_e32 v192, s100, v116
	s_waitcnt vmcnt(20)
	v_mul_f32_e32 v196, s100, v120
	v_cvt_pk_fp8_f32 v180, v192, v196
	s_waitcnt vmcnt(19)
	v_mul_f32_e32 v116, s100, v124
	s_waitcnt vmcnt(18)
	v_mul_f32_e32 v120, s100, v128
	s_waitcnt vmcnt(17)
	v_mul_f32_e32 v192, s100, v132
	v_cvt_pk_fp8_f32 v180, v116, v120 op_sel:[0,0,1]
	s_waitcnt vmcnt(16)
	v_mul_f32_e32 v196, s100, v136
	v_cvt_pk_fp8_f32 v181, v192, v196
	s_waitcnt vmcnt(15)
	v_mul_f32_e32 v192, s100, v140
	s_waitcnt vmcnt(14)
	v_mul_f32_e32 v196, s100, v144
	v_cvt_pk_fp8_f32 v181, v192, v196 op_sel:[0,0,1]
	s_waitcnt vmcnt(13)
	v_mul_f32_e32 v192, s100, v148
	s_waitcnt vmcnt(12)
	v_mul_f32_e32 v196, s100, v152
	v_cvt_pk_fp8_f32 v182, v192, v196
	s_waitcnt vmcnt(11)
	v_mul_f32_e32 v116, s100, v156
	s_waitcnt vmcnt(10)
	v_mul_f32_e32 v120, s100, v160
	s_waitcnt vmcnt(9)
	v_mul_f32_e32 v192, s100, v164
	v_cvt_pk_fp8_f32 v182, v116, v120 op_sel:[0,0,1]
	v_mul_f32_e32 v116, s100, v125
	v_mul_f32_e32 v120, s100, v159
	s_waitcnt vmcnt(8)
	v_mul_f32_e32 v196, s100, v168
	v_cvt_pk_fp8_f32 v183, v192, v196
	s_waitcnt vmcnt(7)
	v_mul_f32_e32 v192, s100, v172
	s_waitcnt vmcnt(6)
	v_mul_f32_e32 v196, s100, v176
	v_cvt_pk_fp8_f32 v183, v192, v196 op_sel:[0,0,1]
	v_mul_f32_e32 v192, s100, v117
	v_mul_f32_e32 v196, s100, v121
	v_cvt_pk_fp8_f32 v184, v192, v196
	v_mul_f32_e32 v192, s100, v133
	v_mul_f32_e32 v196, s100, v137
	v_cvt_pk_fp8_f32 v185, v192, v196
	v_mul_f32_e32 v192, s100, v141
	v_mul_f32_e32 v196, s100, v145
	v_mul_f32_e32 v117, s100, v129
	v_cvt_pk_fp8_f32 v185, v192, v196 op_sel:[0,0,1]
	v_mul_f32_e32 v192, s100, v149
	v_mul_f32_e32 v196, s100, v153
	v_cvt_pk_fp8_f32 v186, v192, v196
	v_mul_f32_e32 v192, s100, v165
	v_mul_f32_e32 v196, s100, v169
	v_cvt_pk_fp8_f32 v187, v192, v196
	v_mul_f32_e32 v192, s100, v173
	v_mul_f32_e32 v196, s100, v177
	v_cvt_pk_fp8_f32 v184, v116, v117 op_sel:[0,0,1]
	v_cvt_pk_fp8_f32 v187, v192, v196 op_sel:[0,0,1]
	v_mul_f32_e32 v192, s100, v118
	v_mul_f32_e32 v196, s100, v122
	v_cvt_pk_fp8_f32 v188, v192, v196
	v_mul_f32_e32 v192, s100, v134
	v_mul_f32_e32 v196, s100, v138
	v_cvt_pk_fp8_f32 v189, v192, v196
	v_mul_f32_e32 v192, s100, v142
	v_mul_f32_e32 v196, s100, v146
	v_mul_f32_e32 v116, s100, v157
	v_cvt_pk_fp8_f32 v189, v192, v196 op_sel:[0,0,1]
	v_mul_f32_e32 v192, s100, v150
	v_mul_f32_e32 v196, s100, v154
	v_cvt_pk_fp8_f32 v190, v192, v196
	v_mul_f32_e32 v192, s100, v166
	v_mul_f32_e32 v196, s100, v170
	v_cvt_pk_fp8_f32 v191, v192, v196
	v_mul_f32_e32 v117, s100, v161
	v_cvt_pk_fp8_f32 v186, v116, v117 op_sel:[0,0,1]
	v_mul_f32_e32 v116, s100, v126
	v_mul_f32_e32 v117, s100, v130
	v_cvt_pk_fp8_f32 v188, v116, v117 op_sel:[0,0,1]
	v_mul_f32_e32 v116, s100, v158
	v_mul_f32_e32 v117, s100, v162
	v_mul_f32_e32 v192, s100, v174
	v_mul_f32_e32 v196, s100, v178
	v_cvt_pk_fp8_f32 v190, v116, v117 op_sel:[0,0,1]
	v_cvt_pk_fp8_f32 v191, v192, v196 op_sel:[0,0,1]
	v_mul_f32_e32 v192, s100, v119
	v_mul_f32_e32 v196, s100, v123
	v_mov_b32_e32 v116, v11
	v_cvt_pk_fp8_f32 v116, v192, v196
	v_mul_f32_e32 v192, s100, v135
	v_mul_f32_e32 v196, s100, v139
	v_mov_b32_e32 v117, v11
	v_cvt_pk_fp8_f32 v117, v192, v196
	v_mul_f32_e32 v118, s100, v127
	v_mul_f32_e32 v119, s100, v131
	v_mul_f32_e32 v192, s100, v143
	v_mul_f32_e32 v196, s100, v147
	v_cvt_pk_fp8_f32 v116, v118, v119 op_sel:[0,0,1]
	v_cvt_pk_fp8_f32 v117, v192, v196 op_sel:[0,0,1]
	v_mul_f32_e32 v192, s100, v151
	v_mul_f32_e32 v196, s100, v155
	v_mov_b32_e32 v118, v11
	v_cvt_pk_fp8_f32 v118, v192, v196
	v_mul_f32_e32 v192, s100, v167
	v_mul_f32_e32 v196, s100, v171
	v_mov_b32_e32 v119, v11
	v_cvt_pk_fp8_f32 v119, v192, v196
	v_mul_f32_e32 v121, s100, v163
	v_mul_f32_e32 v192, s100, v175
	v_mul_f32_e32 v196, s100, v179
	v_cvt_pk_fp8_f32 v118, v120, v121 op_sel:[0,0,1]
	v_cvt_pk_fp8_f32 v119, v192, v196 op_sel:[0,0,1]
	global_store_dwordx4 v[228:229], v[180:183], off
	global_store_dwordx4 v[228:229], v[184:187], off offset:16
	global_store_dwordx4 v[228:229], v[188:191], off offset:32
	global_store_dwordx4 v[228:229], v[116:119], off offset:48
	s_mov_b32 s99, 0
	s_waitcnt vmcnt(4)
	s_andn2_b32 s12, 1, s64
	s_mulk_i32 s12, 0x4600
	s_add_i32 s12, s12, 0
	v_add_u32_e32 v10, s12, v33
	v_add3_u32 v22, s12, v31, v32
	v_add3_u32 v10, v10, v34, s34
	ds_write_b128 v22, v[0:3]
	ds_write2_b64 v10, v[4:5], v[6:7] offset1:1
	s_branch .LBB0_2376
